# v22: v21 + write-through (sc1) stores for the SwiGLU hidden activations
# speedup vs baseline: 1.0112x; 1.0030x over previous
; __device__ __forceinline__ float fsilu(float v) { return v * fsig(v); }
; __device__ __forceinline__ void rstd8(const float* ss, int row0, float sc, float (&rs)[2][4]) {
;     f32x4 pa[2][4];
; #pragma unroll
;     for (int ai = 0; ai < 2; ++ai)
; #pragma unroll
;         for (int m = 0; m < 4; ++m) pa[ai][m] = *(const f32x4*)(ss + (size_t)(row0 + ai * HALF + m * 16) * 4);
; #pragma unroll
;     for (int ai = 0; ai < 2; ++ai)
; #pragma unroll
;         for (int m = 0; m < 4; ++m) { const f32x4 a = pa[ai][m]; rs[ai][m] = rsqrtf(((a[0] + a[1]) + (a[2] + a[3])) * (1.0f / 1024.0f) + 1e-6f) * sc; }
;     __device__ __forceinline__ void operator()(const f32x4 (&acc)[2][2][4][2], const Unit& u, int wr, int wc, int fr, int fq) const {
;     ...
;             for (int m = 0; m < 4; ++m) { const int row = row0 + ai * HALF + m * 16; const float rs = rsv[ai][m];
;                 f32x4 o0, o1;
; #pragma unroll
;                 for (int i = 0; i < 4; ++i) { o0[i] = fsilu(acc[ai][0][m][0][i] * rs) * (acc[ai][1][m][0][i] * rs); o1[i] = fsilu(acc[ai][0][m][1][i] * rs) * (acc[ai][1][m][1][i] * rs); }
.LBB0_307:
	v_lshl_add_u32 v178, s0, 8, v171
	v_lshl_or_b32 v180, s1, 7, v177
	v_readlane_b32 s0, v254, 60
	v_add_u32_e32 v158, 0xb0, v178
	v_ashrrev_i32_e32 v179, 31, v178
	v_readlane_b32 s1, v254, 61
	v_or_b32_e32 v172, 16, v178
	v_ashrrev_i32_e32 v159, 31, v158
	v_lshl_add_u64 v[130:131], v[178:179], 4, s[0:1]
	v_ashrrev_i32_e32 v173, 31, v172
	v_lshl_add_u64 v[134:135], v[158:159], 4, s[0:1]
	global_load_dwordx4 v[184:187], v[130:131], off
	v_or_b32_e32 v168, 32, v178
	global_load_dwordx4 v[134:137], v[134:135], off
	v_lshl_add_u64 v[130:131], v[172:173], 4, s[0:1]
	global_load_dwordx4 v[188:191], v[130:131], off
	v_ashrrev_i32_e32 v169, 31, v168
	v_or_b32_e32 v166, 48, v178
	v_lshl_add_u64 v[130:131], v[168:169], 4, s[0:1]
	v_ashrrev_i32_e32 v167, 31, v166
	global_load_dwordx4 v[192:195], v[130:131], off
	v_lshl_add_u64 v[130:131], v[166:167], 4, s[0:1]
	global_load_dwordx4 v[210:213], v[130:131], off
	v_add_u32_e32 v164, 0x80, v178
	v_ashrrev_i32_e32 v165, 31, v164
	v_add_u32_e32 v162, 0x90, v178
	v_lshl_add_u64 v[130:131], v[164:165], 4, s[0:1]
	v_ashrrev_i32_e32 v163, 31, v162
	global_load_dwordx4 v[142:145], v[130:131], off
	v_lshl_add_u64 v[130:131], v[162:163], 4, s[0:1]
	global_load_dwordx4 v[138:141], v[130:131], off
	v_add_u32_e32 v160, 0xa0, v178
	v_ashrrev_i32_e32 v161, 31, v160
	v_lshl_add_u64 v[130:131], v[160:161], 4, s[0:1]
	global_load_dwordx4 v[130:133], v[130:131], off
	s_waitcnt vmcnt(0)
	v_mov_b32_e32 v214, v185
	v_mov_b32_e32 v215, v186
	v_mov_b32_e32 v185, v187
	v_pk_add_f32 v[184:185], v[214:215], v[184:185]
	v_mov_b32_e32 v186, v189
	v_mov_b32_e32 v187, v190
	v_mov_b32_e32 v189, v191
	v_pk_add_f32 v[186:187], v[186:187], v[188:189]
	v_mov_b32_e32 v189, v184
	v_mov_b32_e32 v188, v186
	v_mov_b32_e32 v184, v187
	v_pk_add_f32 v[186:187], v[188:189], v[184:185]
	v_mov_b64_e32 v[184:185], s[52:53]
	v_pk_fma_f32 v[186:187], v[186:187], s[42:43], v[184:185] op_sel_hi:[1,0,0]
	v_mov_b32_e32 v188, v211
	v_mul_f32_e32 v64, 0x4b800000, v187
	v_cmp_gt_f32_e64 s[0:1], s28, v187
	v_cmp_gt_f32_e32 vcc, s28, v186
	v_mov_b32_e32 v189, v212
	v_cndmask_b32_e64 v64, v187, v64, s[0:1]
	v_rsq_f32_e32 v64, v64
	v_mov_b32_e32 v187, v194
	v_mov_b32_e32 v211, v213
	v_pk_add_f32 v[188:189], v[188:189], v[210:211]
	v_mul_f32_e32 v159, 0x45800000, v64
	v_cndmask_b32_e64 v182, v64, v159, s[0:1]
	v_mul_f32_e32 v64, 0x4b800000, v186
	v_cndmask_b32_e32 v64, v186, v64, vcc
	v_rsq_f32_e32 v64, v64
	v_mov_b32_e32 v186, v193
	v_mov_b32_e32 v193, v195
	v_pk_add_f32 v[186:187], v[186:187], v[192:193]
	v_mov_b32_e32 v190, v188
	v_mov_b32_e32 v191, v186
	v_mov_b32_e32 v186, v189
	v_pk_add_f32 v[186:187], v[190:191], v[186:187]
	v_mul_f32_e32 v159, 0x45800000, v64
	v_pk_fma_f32 v[186:187], v[186:187], s[42:43], v[184:185] op_sel_hi:[1,0,0]
	v_cndmask_b32_e32 v176, v64, v159, vcc
	v_mul_f32_e32 v64, 0x4b800000, v187
	v_cmp_gt_f32_e64 s[0:1], s28, v187
	v_cmp_gt_f32_e32 vcc, s28, v186
	s_nop 0
	v_cndmask_b32_e64 v64, v187, v64, s[0:1]
	v_rsq_f32_e32 v64, v64
	v_mov_b32_e32 v187, v144
	v_mov_b32_e32 v144, v139
	v_mov_b32_e32 v139, v141
	v_mul_f32_e32 v159, 0x45800000, v64
	v_cndmask_b32_e64 v174, v64, v159, s[0:1]
	v_mul_f32_e32 v64, 0x4b800000, v186
	v_cndmask_b32_e32 v64, v186, v64, vcc
	v_rsq_f32_e32 v64, v64
	v_mov_b32_e32 v186, v143
	v_mov_b32_e32 v143, v145
	v_mov_b32_e32 v145, v140
	v_pk_add_f32 v[142:143], v[186:187], v[142:143]
	v_pk_add_f32 v[138:139], v[144:145], v[138:139]
	v_mov_b32_e32 v141, v142
	v_mov_b32_e32 v140, v138
	v_mov_b32_e32 v142, v139
	v_pk_add_f32 v[138:139], v[140:141], v[142:143]
	v_mul_f32_e32 v159, 0x45800000, v64
	v_pk_fma_f32 v[138:139], v[138:139], s[42:43], v[184:185] op_sel_hi:[1,0,0]
	v_cndmask_b32_e32 v170, v64, v159, vcc
	v_mul_f32_e32 v64, 0x4b800000, v139
	v_cmp_gt_f32_e64 s[0:1], s28, v139
	v_cmp_gt_f32_e32 vcc, s28, v138
	v_mov_b32_e32 v142, v131
	v_cndmask_b32_e64 v64, v139, v64, s[0:1]
	v_rsq_f32_e32 v64, v64
	v_mov_b32_e32 v143, v132
	v_mov_b32_e32 v131, v133
	v_mov_b32_e32 v132, v135
	v_mul_f32_e32 v139, 0x45800000, v64
	v_cndmask_b32_e64 v140, v64, v139, s[0:1]
	v_mul_f32_e32 v64, 0x4b800000, v138
	v_cndmask_b32_e32 v64, v138, v64, vcc
	v_rsq_f32_e32 v64, v64
	v_mov_b32_e32 v133, v136
	v_mov_b32_e32 v135, v137
	v_pk_add_f32 v[130:131], v[142:143], v[130:131]
	v_pk_add_f32 v[132:133], v[132:133], v[134:135]
	v_mov_b32_e32 v135, v130
	v_mov_b32_e32 v134, v132
	v_mov_b32_e32 v130, v133
	v_pk_add_f32 v[130:131], v[134:135], v[130:131]
	v_mul_f32_e32 v138, 0x45800000, v64
	v_pk_fma_f32 v[132:133], v[130:131], s[42:43], v[184:185] op_sel_hi:[1,0,0]
	v_cndmask_b32_e32 v138, v64, v138, vcc
	v_mul_f32_e32 v64, 0x4b800000, v133
	v_cmp_gt_f32_e64 s[0:1], s28, v133
	v_cmp_gt_f32_e32 vcc, s28, v132
	s_nop 0
	v_cndmask_b32_e64 v64, v133, v64, s[0:1]
	v_rsq_f32_e32 v64, v64
	s_nop 0
	v_mul_f32_e32 v130, 0x45800000, v64
	v_cndmask_b32_e64 v130, v64, v130, s[0:1]
	v_mul_f32_e32 v64, 0x4b800000, v132
	v_cndmask_b32_e32 v64, v132, v64, vcc
	v_rsq_f32_e32 v64, v64
	s_nop 0
	v_mul_f32_e32 v131, 0x45800000, v64
	v_cndmask_b32_e32 v64, v64, v131, vcc
	v_mov_b32_e32 v132, v118
	v_mov_b32_e32 v133, v126
	v_pk_mul_f32 v[132:133], v[132:133], v[182:183] op_sel_hi:[1,0]
	v_mov_b32_e32 v126, v119
	v_mul_f32_e32 v118, 0xbfb8aa3b, v133
	v_exp_f32_e32 v118, v118
	v_readlane_b32 s0, v254, 9
	v_readlane_b32 s1, v254, 10
	v_ashrrev_i32_e32 v181, 31, v180
	v_add_f32_e32 v118, 1.0, v118
	v_rcp_f32_e32 v118, v118
	s_movk_i32 s6, 0x1600
	v_mul_f32_e32 v118, v133, v118
	v_mul_f32_e32 v131, v132, v118
	v_mov_b32_e32 v132, v114
	v_mov_b32_e32 v133, v122
	v_pk_mul_f32 v[132:133], v[132:133], v[182:183] op_sel_hi:[1,0]
; __device__ __forceinline__ float fsilu(float v) { return v * fsig(v); }
; __device__ __forceinline__ u32x4 pack8(const f32x4 v0, const f32x4 v1) { u32x4 w; w.x = cvt_pk_bf16(v0[0], v0[1]); w.y = cvt_pk_bf16(v0[2], v0[3]); w.z = cvt_pk_bf16(v1[0], v1[1]); w.w = cvt_pk_bf16(v1[2], v1[3]); return w; }
;     __device__ __forceinline__ void operator()(const f32x4 (&acc)[2][2][4][2], const Unit& u, int wr, int wc, int fr, int fq) const {
;     ...
;             for (int m = 0; m < 4; ++m) { const int row = row0 + ai * HALF + m * 16; const float rs = rsv[ai][m];
;                 f32x4 o0, o1;
; #pragma unroll
;                 for (int i = 0; i < 4; ++i) { o0[i] = fsilu(acc[ai][0][m][0][i] * rs) * (acc[ai][1][m][0][i] * rs); o1[i] = fsilu(acc[ai][0][m][1][i] * rs) * (acc[ai][1][m][1][i] * rs); }
;                 *(u32x4*)(H + (size_t)row * ldh + col0) = pack8(o0, o1); __builtin_amdgcn_sched_barrier(0); }
	v_pk_mul_f32 v[118:119], v[126:127], v[182:183] op_sel_hi:[1,0]
	v_mul_f32_e32 v114, 0xbfb8aa3b, v133
	v_exp_f32_e32 v114, v114
	v_mov_b32_e32 v122, v115
	v_add_f32_e32 v114, 1.0, v114
	v_rcp_f32_e32 v114, v114
	s_nop 0
	v_mul_f32_e32 v114, v133, v114
	v_mul_f32_e32 v132, v132, v114
	v_mul_f32_e32 v114, 0xbfb8aa3b, v119
	v_exp_f32_e32 v114, v114
	s_nop 0
	v_add_f32_e32 v114, 1.0, v114
	v_rcp_f32_e32 v114, v114
	s_nop 0
	v_mul_f32_e32 v114, v119, v114
	v_mul_f32_e32 v118, v118, v114
	v_pk_mul_f32 v[114:115], v[122:123], v[182:183] op_sel_hi:[1,0]
	v_cvt_pk_bf16_f32 v118, v131, v118
	s_nop 0
	v_mul_f32_e32 v119, 0xbfb8aa3b, v115
	v_exp_f32_e32 v119, v119
	s_nop 0
	v_add_f32_e32 v119, 1.0, v119
	v_rcp_f32_e32 v119, v119
	s_nop 0
	v_mul_f32_e32 v115, v115, v119
	v_mul_f32_e32 v122, v114, v115
	v_mov_b32_e32 v114, v120
	v_mov_b32_e32 v115, v128
	v_pk_mul_f32 v[114:115], v[114:115], v[182:183] op_sel_hi:[1,0]
	v_mov_b32_e32 v128, v121
	v_mul_f32_e32 v119, 0xbfb8aa3b, v115
	v_exp_f32_e32 v119, v119
	s_nop 0
	v_add_f32_e32 v119, 1.0, v119
	v_rcp_f32_e32 v119, v119
	s_nop 0
	v_mul_f32_e32 v115, v115, v119
	v_mul_f32_e32 v119, v114, v115
	v_mov_b32_e32 v114, v116
	v_mov_b32_e32 v115, v124
	v_pk_mul_f32 v[114:115], v[114:115], v[182:183] op_sel_hi:[1,0]
	v_mov_b32_e32 v124, v117
	v_mul_f32_e32 v116, 0xbfb8aa3b, v115
	v_exp_f32_e32 v116, v116
	s_nop 0
	v_add_f32_e32 v116, 1.0, v116
	v_rcp_f32_e32 v116, v116
	s_nop 0
	v_mul_f32_e32 v115, v115, v116
	v_mul_f32_e32 v116, v114, v115
	v_pk_mul_f32 v[114:115], v[128:129], v[182:183] op_sel_hi:[1,0]
	s_nop 0
	v_mul_f32_e32 v120, 0xbfb8aa3b, v115
	v_exp_f32_e32 v120, v120
	s_nop 0
	v_add_f32_e32 v120, 1.0, v120
	v_rcp_f32_e32 v120, v120
	s_nop 0
	v_mul_f32_e32 v115, v115, v120
	v_mul_f32_e32 v120, v114, v115
	v_pk_mul_f32 v[114:115], v[124:125], v[182:183] op_sel_hi:[1,0]
	v_cvt_pk_bf16_f32 v119, v119, v120
	v_cvt_pk_bf16_f32 v120, v132, v122
	s_nop 0
	v_mul_f32_e32 v117, 0xbfb8aa3b, v115
	v_exp_f32_e32 v117, v117
	s_nop 0
	v_add_f32_e32 v117, 1.0, v117
	v_rcp_f32_e32 v117, v117
	s_nop 0
	v_mul_f32_e32 v115, v115, v117
	v_mul_f32_e32 v114, v114, v115
	v_cvt_pk_bf16_f32 v121, v116, v114
	v_mov_b64_e32 v[114:115], s[0:1]
	v_mad_i64_i32 v[122:123], s[0:1], v178, s6, v[114:115]
	v_lshlrev_b64 v[116:117], 1, v[180:181]
	v_lshl_add_u64 v[122:123], v[122:123], 0, v[116:117]
	global_store_dwordx4 v[122:123], v[118:121], off sc1
	s_nop 1
	v_mov_b32_e32 v118, v102
	v_mov_b32_e32 v119, v110
	v_pk_mul_f32 v[118:119], v[118:119], v[176:177] op_sel_hi:[1,0]
	v_mov_b32_e32 v110, v103
	v_mul_f32_e32 v102, 0xbfb8aa3b, v119
	v_exp_f32_e32 v102, v102
	s_nop 0
	v_add_f32_e32 v102, 1.0, v102
	v_rcp_f32_e32 v102, v102
	s_nop 0
	v_mul_f32_e32 v102, v119, v102
	v_mul_f32_e32 v120, v118, v102
	v_mov_b32_e32 v118, v98
	v_mov_b32_e32 v119, v106
	v_pk_mul_f32 v[118:119], v[118:119], v[176:177] op_sel_hi:[1,0]
	v_pk_mul_f32 v[102:103], v[110:111], v[176:177] op_sel_hi:[1,0]
	v_mul_f32_e32 v98, 0xbfb8aa3b, v119
	v_exp_f32_e32 v98, v98
	v_mov_b32_e32 v106, v99
	v_add_f32_e32 v98, 1.0, v98
	v_rcp_f32_e32 v98, v98
	s_nop 0
	v_mul_f32_e32 v98, v119, v98
	v_mul_f32_e32 v118, v118, v98
	v_mul_f32_e32 v98, 0xbfb8aa3b, v103
	v_exp_f32_e32 v98, v98
	s_nop 0
	v_add_f32_e32 v98, 1.0, v98
	v_rcp_f32_e32 v98, v98
	s_nop 0
	v_mul_f32_e32 v98, v103, v98
	v_mul_f32_e32 v102, v102, v98
	v_pk_mul_f32 v[98:99], v[106:107], v[176:177] op_sel_hi:[1,0]
	s_nop 0
	v_mul_f32_e32 v103, 0xbfb8aa3b, v99
	v_exp_f32_e32 v103, v103
	s_nop 0
	v_add_f32_e32 v103, 1.0, v103
	v_rcp_f32_e32 v103, v103
	s_nop 0
	v_mul_f32_e32 v99, v99, v103
	v_mul_f32_e32 v103, v98, v99
	v_mov_b32_e32 v98, v104
	v_mov_b32_e32 v99, v112
	v_pk_mul_f32 v[98:99], v[98:99], v[176:177] op_sel_hi:[1,0]
	v_mov_b32_e32 v112, v105
	v_mul_f32_e32 v104, 0xbfb8aa3b, v99
	v_exp_f32_e32 v104, v104
	s_nop 0
	v_add_f32_e32 v104, 1.0, v104
	v_rcp_f32_e32 v104, v104
	s_nop 0
	v_mul_f32_e32 v99, v99, v104
	v_mul_f32_e32 v104, v98, v99
	v_mov_b32_e32 v98, v100
	v_mov_b32_e32 v99, v108
	v_pk_mul_f32 v[98:99], v[98:99], v[176:177] op_sel_hi:[1,0]
	v_mov_b32_e32 v108, v101
	v_mul_f32_e32 v100, 0xbfb8aa3b, v99
	v_exp_f32_e32 v100, v100
	s_nop 0
	v_add_f32_e32 v100, 1.0, v100
	v_rcp_f32_e32 v100, v100
	s_nop 0
	v_mul_f32_e32 v99, v99, v100
	v_mul_f32_e32 v106, v98, v99
	v_pk_mul_f32 v[98:99], v[112:113], v[176:177] op_sel_hi:[1,0]
	s_nop 0
	v_mul_f32_e32 v100, 0xbfb8aa3b, v99
	v_exp_f32_e32 v100, v100
	s_nop 0
	v_add_f32_e32 v100, 1.0, v100
	v_rcp_f32_e32 v100, v100
	s_nop 0
	v_mul_f32_e32 v99, v99, v100
	v_mul_f32_e32 v100, v98, v99
	v_pk_mul_f32 v[98:99], v[108:109], v[176:177] op_sel_hi:[1,0]
	s_nop 0
	v_mul_f32_e32 v101, 0xbfb8aa3b, v99
	v_exp_f32_e32 v101, v101
	s_nop 0
	v_add_f32_e32 v101, 1.0, v101
	v_rcp_f32_e32 v101, v101
	s_nop 0
	v_mul_f32_e32 v99, v99, v101
	v_mul_f32_e32 v101, v98, v99
	v_cvt_pk_bf16_f32 v98, v120, v102
	v_cvt_pk_bf16_f32 v99, v104, v100
	v_cvt_pk_bf16_f32 v100, v118, v103
	v_mad_i64_i32 v[102:103], s[0:1], v172, s6, v[114:115]
	v_lshl_add_u64 v[102:103], v[102:103], 0, v[116:117]
	v_cvt_pk_bf16_f32 v101, v106, v101
	global_store_dwordx4 v[102:103], v[98:101], off sc1
	s_nop 1
	v_mov_b32_e32 v98, v86
	v_mov_b32_e32 v99, v94
	v_pk_mul_f32 v[98:99], v[98:99], v[174:175] op_sel_hi:[1,0]
	v_mov_b32_e32 v94, v87
	v_mul_f32_e32 v86, 0xbfb8aa3b, v99
	v_exp_f32_e32 v86, v86
	s_nop 0
	v_add_f32_e32 v86, 1.0, v86
	v_rcp_f32_e32 v86, v86
	s_nop 0
	v_mul_f32_e32 v86, v99, v86
	v_mul_f32_e32 v100, v98, v86
	v_mov_b32_e32 v98, v82
	v_mov_b32_e32 v99, v90
	v_pk_mul_f32 v[98:99], v[98:99], v[174:175] op_sel_hi:[1,0]
	v_pk_mul_f32 v[86:87], v[94:95], v[174:175] op_sel_hi:[1,0]
	v_mul_f32_e32 v82, 0xbfb8aa3b, v99
; __device__ __forceinline__ float fsilu(float v) { return v * fsig(v); }
; __device__ __forceinline__ u32x4 pack8(const f32x4 v0, const f32x4 v1) { u32x4 w; w.x = cvt_pk_bf16(v0[0], v0[1]); w.y = cvt_pk_bf16(v0[2], v0[3]); w.z = cvt_pk_bf16(v1[0], v1[1]); w.w = cvt_pk_bf16(v1[2], v1[3]); return w; }
;     __device__ __forceinline__ void operator()(const f32x4 (&acc)[2][2][4][2], const Unit& u, int wr, int wc, int fr, int fq) const {
;     ...
;             for (int m = 0; m < 4; ++m) { const int row = row0 + ai * HALF + m * 16; const float rs = rsv[ai][m];
;                 f32x4 o0, o1;
; #pragma unroll
;                 for (int i = 0; i < 4; ++i) { o0[i] = fsilu(acc[ai][0][m][0][i] * rs) * (acc[ai][1][m][0][i] * rs); o1[i] = fsilu(acc[ai][0][m][1][i] * rs) * (acc[ai][1][m][1][i] * rs); }
;                 *(u32x4*)(H + (size_t)row * ldh + col0) = pack8(o0, o1); __builtin_amdgcn_sched_barrier(0); }
	v_exp_f32_e32 v82, v82
	v_mov_b32_e32 v90, v83
	v_add_f32_e32 v82, 1.0, v82
	v_rcp_f32_e32 v82, v82
	s_nop 0
	v_mul_f32_e32 v82, v99, v82
	v_mul_f32_e32 v98, v98, v82
	v_mul_f32_e32 v82, 0xbfb8aa3b, v87
	v_exp_f32_e32 v82, v82
	s_nop 0
	v_add_f32_e32 v82, 1.0, v82
	v_rcp_f32_e32 v82, v82
	s_nop 0
	v_mul_f32_e32 v82, v87, v82
	v_mul_f32_e32 v86, v86, v82
	v_pk_mul_f32 v[82:83], v[90:91], v[174:175] op_sel_hi:[1,0]
	s_nop 0
	v_mul_f32_e32 v87, 0xbfb8aa3b, v83
	v_exp_f32_e32 v87, v87
	s_nop 0
	v_add_f32_e32 v87, 1.0, v87
	v_rcp_f32_e32 v87, v87
	s_nop 0
	v_mul_f32_e32 v83, v83, v87
	v_mul_f32_e32 v87, v82, v83
	v_mov_b32_e32 v82, v88
	v_mov_b32_e32 v83, v96
	v_pk_mul_f32 v[82:83], v[82:83], v[174:175] op_sel_hi:[1,0]
	v_mov_b32_e32 v96, v89
	v_mul_f32_e32 v88, 0xbfb8aa3b, v83
	v_exp_f32_e32 v88, v88
	s_nop 0
	v_add_f32_e32 v88, 1.0, v88
	v_rcp_f32_e32 v88, v88
	s_nop 0
	v_mul_f32_e32 v83, v83, v88
	v_mul_f32_e32 v88, v82, v83
	v_mov_b32_e32 v82, v84
	v_mov_b32_e32 v83, v92
	v_pk_mul_f32 v[82:83], v[82:83], v[174:175] op_sel_hi:[1,0]
	v_mov_b32_e32 v92, v85
	v_mul_f32_e32 v84, 0xbfb8aa3b, v83
	v_exp_f32_e32 v84, v84
	s_nop 0
	v_add_f32_e32 v84, 1.0, v84
	v_rcp_f32_e32 v84, v84
	s_nop 0
	v_mul_f32_e32 v83, v83, v84
	v_mul_f32_e32 v90, v82, v83
	v_pk_mul_f32 v[82:83], v[96:97], v[174:175] op_sel_hi:[1,0]
	s_nop 0
	v_mul_f32_e32 v84, 0xbfb8aa3b, v83
	v_exp_f32_e32 v84, v84
	s_nop 0
	v_add_f32_e32 v84, 1.0, v84
	v_rcp_f32_e32 v84, v84
	s_nop 0
	v_mul_f32_e32 v83, v83, v84
	v_mul_f32_e32 v84, v82, v83
	v_pk_mul_f32 v[82:83], v[92:93], v[174:175] op_sel_hi:[1,0]
	s_nop 0
	v_mul_f32_e32 v85, 0xbfb8aa3b, v83
	v_exp_f32_e32 v85, v85
	s_nop 0
	v_add_f32_e32 v85, 1.0, v85
	v_rcp_f32_e32 v85, v85
	s_nop 0
	v_mul_f32_e32 v83, v83, v85
	v_mul_f32_e32 v85, v82, v83
	v_cvt_pk_bf16_f32 v82, v100, v86
	v_cvt_pk_bf16_f32 v83, v88, v84
	v_cvt_pk_bf16_f32 v84, v98, v87
	v_mad_i64_i32 v[86:87], s[0:1], v168, s6, v[114:115]
	v_lshl_add_u64 v[86:87], v[86:87], 0, v[116:117]
	v_cvt_pk_bf16_f32 v85, v90, v85
	global_store_dwordx4 v[86:87], v[82:85], off sc1
	s_nop 1
	v_mov_b32_e32 v82, v70
	v_mov_b32_e32 v83, v78
	v_pk_mul_f32 v[82:83], v[82:83], v[170:171] op_sel_hi:[1,0]
	v_mov_b32_e32 v78, v71
	v_mul_f32_e32 v70, 0xbfb8aa3b, v83
	v_exp_f32_e32 v70, v70
	s_nop 0
	v_add_f32_e32 v70, 1.0, v70
	v_rcp_f32_e32 v70, v70
	s_nop 0
	v_mul_f32_e32 v70, v83, v70
	v_mul_f32_e32 v84, v82, v70
	v_mov_b32_e32 v82, v66
	v_mov_b32_e32 v83, v74
	v_pk_mul_f32 v[82:83], v[82:83], v[170:171] op_sel_hi:[1,0]
	v_pk_mul_f32 v[70:71], v[78:79], v[170:171] op_sel_hi:[1,0]
	v_mul_f32_e32 v66, 0xbfb8aa3b, v83
	v_exp_f32_e32 v66, v66
	v_mov_b32_e32 v74, v67
	v_add_f32_e32 v66, 1.0, v66
	v_rcp_f32_e32 v66, v66
	s_nop 0
	v_mul_f32_e32 v66, v83, v66
	v_mul_f32_e32 v82, v82, v66
	v_mul_f32_e32 v66, 0xbfb8aa3b, v71
	v_exp_f32_e32 v66, v66
	s_nop 0
	v_add_f32_e32 v66, 1.0, v66
	v_rcp_f32_e32 v66, v66
	s_nop 0
	v_mul_f32_e32 v66, v71, v66
	v_mul_f32_e32 v70, v70, v66
	v_pk_mul_f32 v[66:67], v[74:75], v[170:171] op_sel_hi:[1,0]
	s_nop 0
	v_mul_f32_e32 v71, 0xbfb8aa3b, v67
	v_exp_f32_e32 v71, v71
	s_nop 0
	v_add_f32_e32 v71, 1.0, v71
	v_rcp_f32_e32 v71, v71
	s_nop 0
	v_mul_f32_e32 v67, v67, v71
	v_mul_f32_e32 v71, v66, v67
	v_mov_b32_e32 v66, v72
	v_mov_b32_e32 v67, v80
	v_pk_mul_f32 v[66:67], v[66:67], v[170:171] op_sel_hi:[1,0]
	v_mov_b32_e32 v80, v73
	v_mul_f32_e32 v72, 0xbfb8aa3b, v67
	v_exp_f32_e32 v72, v72
	s_nop 0
	v_add_f32_e32 v72, 1.0, v72
	v_rcp_f32_e32 v72, v72
	s_nop 0
	v_mul_f32_e32 v67, v67, v72
	v_mul_f32_e32 v72, v66, v67
	v_mov_b32_e32 v66, v68
	v_mov_b32_e32 v67, v76
	v_pk_mul_f32 v[66:67], v[66:67], v[170:171] op_sel_hi:[1,0]
	v_mov_b32_e32 v76, v69
	v_mul_f32_e32 v68, 0xbfb8aa3b, v67
	v_exp_f32_e32 v68, v68
	s_nop 0
	v_add_f32_e32 v68, 1.0, v68
	v_rcp_f32_e32 v68, v68
	s_nop 0
	v_mul_f32_e32 v67, v67, v68
	v_mul_f32_e32 v74, v66, v67
	v_pk_mul_f32 v[66:67], v[80:81], v[170:171] op_sel_hi:[1,0]
	s_nop 0
	v_mul_f32_e32 v68, 0xbfb8aa3b, v67
	v_exp_f32_e32 v68, v68
	s_nop 0
	v_add_f32_e32 v68, 1.0, v68
	v_rcp_f32_e32 v68, v68
	s_nop 0
	v_mul_f32_e32 v67, v67, v68
	v_mul_f32_e32 v68, v66, v67
	v_pk_mul_f32 v[66:67], v[76:77], v[170:171] op_sel_hi:[1,0]
	s_nop 0
	v_mul_f32_e32 v69, 0xbfb8aa3b, v67
	v_exp_f32_e32 v69, v69
	s_nop 0
	v_add_f32_e32 v69, 1.0, v69
	v_rcp_f32_e32 v69, v69
	s_nop 0
	v_mul_f32_e32 v67, v67, v69
	v_mul_f32_e32 v69, v66, v67
	v_cvt_pk_bf16_f32 v66, v84, v70
	v_cvt_pk_bf16_f32 v67, v72, v68
	v_cvt_pk_bf16_f32 v68, v82, v71
	v_mad_i64_i32 v[70:71], s[0:1], v166, s6, v[114:115]
	v_lshl_add_u64 v[70:71], v[70:71], 0, v[116:117]
	v_cvt_pk_bf16_f32 v69, v74, v69
	global_store_dwordx4 v[70:71], v[66:69], off sc1
	s_nop 1
	v_mov_b32_e32 v66, v52
	v_mov_b32_e32 v67, v60
	v_pk_mul_f32 v[66:67], v[66:67], v[140:141] op_sel_hi:[1,0]
	v_mov_b32_e32 v60, v53
	v_mul_f32_e32 v52, 0xbfb8aa3b, v67
	v_exp_f32_e32 v52, v52
	s_nop 0
	v_add_f32_e32 v52, 1.0, v52
	v_rcp_f32_e32 v52, v52
	s_nop 0
	v_mul_f32_e32 v52, v67, v52
	v_mul_f32_e32 v68, v66, v52
	v_mov_b32_e32 v66, v48
	v_mov_b32_e32 v67, v56
	v_pk_mul_f32 v[66:67], v[66:67], v[140:141] op_sel_hi:[1,0]
	v_pk_mul_f32 v[52:53], v[60:61], v[140:141] op_sel_hi:[1,0]
	v_mul_f32_e32 v48, 0xbfb8aa3b, v67
	v_exp_f32_e32 v48, v48
	v_mov_b32_e32 v56, v49
	v_add_f32_e32 v48, 1.0, v48
	v_rcp_f32_e32 v48, v48
	s_nop 0
	v_mul_f32_e32 v48, v67, v48
	v_mul_f32_e32 v66, v66, v48
	v_mul_f32_e32 v48, 0xbfb8aa3b, v53
	v_exp_f32_e32 v48, v48
	s_nop 0
	v_add_f32_e32 v48, 1.0, v48
	v_rcp_f32_e32 v48, v48
	s_nop 0
	v_mul_f32_e32 v48, v53, v48
	v_mul_f32_e32 v52, v52, v48
	v_pk_mul_f32 v[48:49], v[56:57], v[140:141] op_sel_hi:[1,0]
	s_nop 0
; __device__ __forceinline__ float fsilu(float v) { return v * fsig(v); }
; __device__ __forceinline__ u32x4 pack8(const f32x4 v0, const f32x4 v1) { u32x4 w; w.x = cvt_pk_bf16(v0[0], v0[1]); w.y = cvt_pk_bf16(v0[2], v0[3]); w.z = cvt_pk_bf16(v1[0], v1[1]); w.w = cvt_pk_bf16(v1[2], v1[3]); return w; }
;     __device__ __forceinline__ void operator()(const f32x4 (&acc)[2][2][4][2], const Unit& u, int wr, int wc, int fr, int fq) const {
;     ...
;             for (int m = 0; m < 4; ++m) { const int row = row0 + ai * HALF + m * 16; const float rs = rsv[ai][m];
;                 f32x4 o0, o1;
; #pragma unroll
;                 for (int i = 0; i < 4; ++i) { o0[i] = fsilu(acc[ai][0][m][0][i] * rs) * (acc[ai][1][m][0][i] * rs); o1[i] = fsilu(acc[ai][0][m][1][i] * rs) * (acc[ai][1][m][1][i] * rs); }
;                 *(u32x4*)(H + (size_t)row * ldh + col0) = pack8(o0, o1); __builtin_amdgcn_sched_barrier(0); }
	v_mul_f32_e32 v53, 0xbfb8aa3b, v49
	v_exp_f32_e32 v53, v53
	s_nop 0
	v_add_f32_e32 v53, 1.0, v53
	v_rcp_f32_e32 v53, v53
	s_nop 0
	v_mul_f32_e32 v49, v49, v53
	v_mul_f32_e32 v53, v48, v49
	v_mov_b32_e32 v48, v54
	v_mov_b32_e32 v49, v62
	v_pk_mul_f32 v[48:49], v[48:49], v[140:141] op_sel_hi:[1,0]
	v_mov_b32_e32 v62, v55
	v_mul_f32_e32 v54, 0xbfb8aa3b, v49
	v_exp_f32_e32 v54, v54
	s_nop 0
	v_add_f32_e32 v54, 1.0, v54
	v_rcp_f32_e32 v54, v54
	s_nop 0
	v_mul_f32_e32 v49, v49, v54
	v_mul_f32_e32 v54, v48, v49
	v_mov_b32_e32 v48, v50
	v_mov_b32_e32 v49, v58
	v_pk_mul_f32 v[48:49], v[48:49], v[140:141] op_sel_hi:[1,0]
	v_mov_b32_e32 v58, v51
	v_mul_f32_e32 v50, 0xbfb8aa3b, v49
	v_exp_f32_e32 v50, v50
	s_nop 0
	v_add_f32_e32 v50, 1.0, v50
	v_rcp_f32_e32 v50, v50
	s_nop 0
	v_mul_f32_e32 v49, v49, v50
	v_mul_f32_e32 v56, v48, v49
	v_pk_mul_f32 v[48:49], v[62:63], v[140:141] op_sel_hi:[1,0]
	s_nop 0
	v_mul_f32_e32 v50, 0xbfb8aa3b, v49
	v_exp_f32_e32 v50, v50
	s_nop 0
	v_add_f32_e32 v50, 1.0, v50
	v_rcp_f32_e32 v50, v50
	s_nop 0
	v_mul_f32_e32 v49, v49, v50
	v_mul_f32_e32 v50, v48, v49
	v_pk_mul_f32 v[48:49], v[58:59], v[140:141] op_sel_hi:[1,0]
	s_nop 0
	v_mul_f32_e32 v51, 0xbfb8aa3b, v49
	v_exp_f32_e32 v51, v51
	s_nop 0
	v_add_f32_e32 v51, 1.0, v51
	v_rcp_f32_e32 v51, v51
	s_nop 0
	v_mul_f32_e32 v49, v49, v51
	v_mul_f32_e32 v51, v48, v49
	v_cvt_pk_bf16_f32 v48, v68, v52
	v_cvt_pk_bf16_f32 v49, v54, v50
	v_cvt_pk_bf16_f32 v50, v66, v53
	v_mad_i64_i32 v[52:53], s[0:1], v164, s6, v[114:115]
	v_lshl_add_u64 v[52:53], v[52:53], 0, v[116:117]
	v_cvt_pk_bf16_f32 v51, v56, v51
	global_store_dwordx4 v[52:53], v[48:51], off sc1
	s_nop 1
	v_mov_b32_e32 v48, v36
	v_mov_b32_e32 v49, v44
	v_pk_mul_f32 v[48:49], v[48:49], v[138:139] op_sel_hi:[1,0]
	v_mov_b32_e32 v44, v37
	v_mul_f32_e32 v36, 0xbfb8aa3b, v49
	v_exp_f32_e32 v36, v36
	s_nop 0
	v_add_f32_e32 v36, 1.0, v36
	v_rcp_f32_e32 v36, v36
	s_nop 0
	v_mul_f32_e32 v36, v49, v36
	v_mul_f32_e32 v50, v48, v36
	v_mov_b32_e32 v48, v32
	v_mov_b32_e32 v49, v40
	v_pk_mul_f32 v[48:49], v[48:49], v[138:139] op_sel_hi:[1,0]
	v_pk_mul_f32 v[36:37], v[44:45], v[138:139] op_sel_hi:[1,0]
	v_mul_f32_e32 v32, 0xbfb8aa3b, v49
	v_exp_f32_e32 v32, v32
	v_mov_b32_e32 v40, v33
	v_add_f32_e32 v32, 1.0, v32
	v_rcp_f32_e32 v32, v32
	s_nop 0
	v_mul_f32_e32 v32, v49, v32
	v_mul_f32_e32 v48, v48, v32
	v_mul_f32_e32 v32, 0xbfb8aa3b, v37
	v_exp_f32_e32 v32, v32
	s_nop 0
	v_add_f32_e32 v32, 1.0, v32
	v_rcp_f32_e32 v32, v32
	s_nop 0
	v_mul_f32_e32 v32, v37, v32
	v_mul_f32_e32 v36, v36, v32
	v_pk_mul_f32 v[32:33], v[40:41], v[138:139] op_sel_hi:[1,0]
	s_nop 0
	v_mul_f32_e32 v37, 0xbfb8aa3b, v33
	v_exp_f32_e32 v37, v37
	s_nop 0
	v_add_f32_e32 v37, 1.0, v37
	v_rcp_f32_e32 v37, v37
	s_nop 0
	v_mul_f32_e32 v33, v33, v37
	v_mul_f32_e32 v37, v32, v33
	v_mov_b32_e32 v32, v38
	v_mov_b32_e32 v33, v46
	v_pk_mul_f32 v[32:33], v[32:33], v[138:139] op_sel_hi:[1,0]
	v_mov_b32_e32 v46, v39
	v_mul_f32_e32 v38, 0xbfb8aa3b, v33
	v_exp_f32_e32 v38, v38
	s_nop 0
	v_add_f32_e32 v38, 1.0, v38
	v_rcp_f32_e32 v38, v38
	s_nop 0
	v_mul_f32_e32 v33, v33, v38
	v_mul_f32_e32 v38, v32, v33
	v_mov_b32_e32 v32, v34
	v_mov_b32_e32 v33, v42
	v_pk_mul_f32 v[32:33], v[32:33], v[138:139] op_sel_hi:[1,0]
	v_mov_b32_e32 v42, v35
	v_mul_f32_e32 v34, 0xbfb8aa3b, v33
	v_exp_f32_e32 v34, v34
	s_nop 0
	v_add_f32_e32 v34, 1.0, v34
	v_rcp_f32_e32 v34, v34
	s_nop 0
	v_mul_f32_e32 v33, v33, v34
	v_mul_f32_e32 v40, v32, v33
	v_pk_mul_f32 v[32:33], v[46:47], v[138:139] op_sel_hi:[1,0]
	s_nop 0
	v_mul_f32_e32 v34, 0xbfb8aa3b, v33
	v_exp_f32_e32 v34, v34
	s_nop 0
	v_add_f32_e32 v34, 1.0, v34
	v_rcp_f32_e32 v34, v34
	s_nop 0
	v_mul_f32_e32 v33, v33, v34
	v_mul_f32_e32 v34, v32, v33
	v_pk_mul_f32 v[32:33], v[42:43], v[138:139] op_sel_hi:[1,0]
	s_nop 0
	v_mul_f32_e32 v35, 0xbfb8aa3b, v33
	v_exp_f32_e32 v35, v35
	s_nop 0
	v_add_f32_e32 v35, 1.0, v35
	v_rcp_f32_e32 v35, v35
	s_nop 0
	v_mul_f32_e32 v33, v33, v35
	v_mul_f32_e32 v35, v32, v33
	v_cvt_pk_bf16_f32 v32, v50, v36
	v_cvt_pk_bf16_f32 v33, v38, v34
	v_cvt_pk_bf16_f32 v34, v48, v37
	v_mad_i64_i32 v[36:37], s[0:1], v162, s6, v[114:115]
	v_lshl_add_u64 v[36:37], v[36:37], 0, v[116:117]
	v_cvt_pk_bf16_f32 v35, v40, v35
	global_store_dwordx4 v[36:37], v[32:35], off sc1
	s_nop 1
	v_mov_b32_e32 v32, v20
	v_mov_b32_e32 v33, v28
	v_pk_mul_f32 v[32:33], v[32:33], v[130:131] op_sel_hi:[1,0]
	v_mov_b32_e32 v28, v21
	v_mul_f32_e32 v20, 0xbfb8aa3b, v33
	v_exp_f32_e32 v20, v20
	s_nop 0
	v_add_f32_e32 v20, 1.0, v20
	v_rcp_f32_e32 v20, v20
	s_nop 0
	v_mul_f32_e32 v20, v33, v20
	v_mul_f32_e32 v34, v32, v20
	v_mov_b32_e32 v32, v16
	v_mov_b32_e32 v33, v24
	v_pk_mul_f32 v[32:33], v[32:33], v[130:131] op_sel_hi:[1,0]
	v_pk_mul_f32 v[20:21], v[28:29], v[130:131] op_sel_hi:[1,0]
; __device__ __forceinline__ float fsilu(float v) { return v * fsig(v); }
; __device__ __forceinline__ u32x4 pack8(const f32x4 v0, const f32x4 v1) { u32x4 w; w.x = cvt_pk_bf16(v0[0], v0[1]); w.y = cvt_pk_bf16(v0[2], v0[3]); w.z = cvt_pk_bf16(v1[0], v1[1]); w.w = cvt_pk_bf16(v1[2], v1[3]); return w; }
; #define PG8_BAR __builtin_amdgcn_s_barrier()
;     __device__ __forceinline__ void operator()(const f32x4 (&acc)[2][2][4][2], const Unit& u, int wr, int wc, int fr, int fq) const {
;     ...
;             for (int m = 0; m < 4; ++m) { const int row = row0 + ai * HALF + m * 16; const float rs = rsv[ai][m];
;                 f32x4 o0, o1;
; #pragma unroll
;                 for (int i = 0; i < 4; ++i) { o0[i] = fsilu(acc[ai][0][m][0][i] * rs) * (acc[ai][1][m][0][i] * rs); o1[i] = fsilu(acc[ai][0][m][1][i] * rs) * (acc[ai][1][m][1][i] * rs); }
;                 *(u32x4*)(H + (size_t)row * ldh + col0) = pack8(o0, o1); __builtin_amdgcn_sched_barrier(0); }
; template <class Epi, class Sched, bool ALIGN_EPI = false, bool SP2 = false>
; __device__ __forceinline__ void gemm_phase(PG8_LAS unsigned char* lds, const Gemm g, const Sched& S, const Epi& E) {
;     ...
;         if constexpr (!Epi::AFTER_DRAIN) { E(acc, cur, wr, wc, fr, fq); S.done(cur); }
;         if (!has_next) break;
; #pragma unroll
;         for (int a = 0; a < 2; ++a)
; #pragma unroll
;             for (int b = 0; b < 2; ++b)
; #pragma unroll
;                 for (int m = 0; m < 4; ++m)
; #pragma unroll
;                     for (int n = 0; n < 2; ++n) acc[a][b][m][n] = (f32x4){0.f, 0.f, 0.f, 0.f};
;         cur = nxt; cA = nA; cB = nB; ++ui;
;         if constexpr (ALIGN_EPI) { if (wr == 1) PG8_BAR; }
;     }
	v_mul_f32_e32 v16, 0xbfb8aa3b, v33
	v_exp_f32_e32 v16, v16
	v_mov_b32_e32 v24, v17
	v_add_f32_e32 v16, 1.0, v16
	v_rcp_f32_e32 v16, v16
	s_nop 0
	v_mul_f32_e32 v16, v33, v16
	v_mul_f32_e32 v32, v32, v16
	v_mul_f32_e32 v16, 0xbfb8aa3b, v21
	v_exp_f32_e32 v16, v16
	s_nop 0
	v_add_f32_e32 v16, 1.0, v16
	v_rcp_f32_e32 v16, v16
	s_nop 0
	v_mul_f32_e32 v16, v21, v16
	v_mul_f32_e32 v20, v20, v16
	v_pk_mul_f32 v[16:17], v[24:25], v[130:131] op_sel_hi:[1,0]
	s_nop 0
	v_mul_f32_e32 v21, 0xbfb8aa3b, v17
	v_exp_f32_e32 v21, v21
	s_nop 0
	v_add_f32_e32 v21, 1.0, v21
	v_rcp_f32_e32 v21, v21
	s_nop 0
	v_mul_f32_e32 v17, v17, v21
	v_mul_f32_e32 v21, v16, v17
	v_mov_b32_e32 v16, v22
	v_mov_b32_e32 v17, v30
	v_pk_mul_f32 v[16:17], v[16:17], v[130:131] op_sel_hi:[1,0]
	v_mov_b32_e32 v30, v23
	v_mul_f32_e32 v22, 0xbfb8aa3b, v17
	v_exp_f32_e32 v22, v22
	s_nop 0
	v_add_f32_e32 v22, 1.0, v22
	v_rcp_f32_e32 v22, v22
	s_nop 0
	v_mul_f32_e32 v17, v17, v22
	v_mul_f32_e32 v22, v16, v17
	v_mov_b32_e32 v16, v18
	v_mov_b32_e32 v17, v26
	v_pk_mul_f32 v[16:17], v[16:17], v[130:131] op_sel_hi:[1,0]
	v_mov_b32_e32 v26, v19
	v_mul_f32_e32 v18, 0xbfb8aa3b, v17
	v_exp_f32_e32 v18, v18
	s_nop 0
	v_add_f32_e32 v18, 1.0, v18
	v_rcp_f32_e32 v18, v18
	s_nop 0
	v_mul_f32_e32 v17, v17, v18
	v_mul_f32_e32 v24, v16, v17
	v_pk_mul_f32 v[16:17], v[30:31], v[130:131] op_sel_hi:[1,0]
	s_nop 0
	v_mul_f32_e32 v18, 0xbfb8aa3b, v17
	v_exp_f32_e32 v18, v18
	s_nop 0
	v_add_f32_e32 v18, 1.0, v18
	v_rcp_f32_e32 v18, v18
	s_nop 0
	v_mul_f32_e32 v17, v17, v18
	v_mul_f32_e32 v18, v16, v17
	v_pk_mul_f32 v[16:17], v[26:27], v[130:131] op_sel_hi:[1,0]
	s_nop 0
	v_mul_f32_e32 v19, 0xbfb8aa3b, v17
	v_exp_f32_e32 v19, v19
	s_nop 0
	v_add_f32_e32 v19, 1.0, v19
	v_rcp_f32_e32 v19, v19
	s_nop 0
	v_mul_f32_e32 v17, v17, v19
	v_mul_f32_e32 v19, v16, v17
	v_cvt_pk_bf16_f32 v16, v34, v20
	v_cvt_pk_bf16_f32 v17, v22, v18
	v_cvt_pk_bf16_f32 v18, v32, v21
	v_mad_i64_i32 v[20:21], s[0:1], v160, s6, v[114:115]
	v_lshl_add_u64 v[20:21], v[20:21], 0, v[116:117]
	v_cvt_pk_bf16_f32 v19, v24, v19
	global_store_dwordx4 v[20:21], v[16:19], off sc1
	s_nop 1
	v_mov_b32_e32 v16, v4
	v_mov_b32_e32 v17, v12
	v_pk_mul_f32 v[16:17], v[16:17], v[64:65] op_sel_hi:[1,0]
	v_mov_b32_e32 v12, v5
	v_mul_f32_e32 v4, 0xbfb8aa3b, v17
	v_exp_f32_e32 v4, v4
	s_nop 0
	v_add_f32_e32 v4, 1.0, v4
	v_rcp_f32_e32 v4, v4
	s_nop 0
	v_mul_f32_e32 v4, v17, v4
	v_mul_f32_e32 v18, v16, v4
	v_mov_b32_e32 v16, v0
	v_mov_b32_e32 v17, v8
	v_pk_mul_f32 v[16:17], v[16:17], v[64:65] op_sel_hi:[1,0]
	v_pk_mul_f32 v[4:5], v[12:13], v[64:65] op_sel_hi:[1,0]
	v_mul_f32_e32 v0, 0xbfb8aa3b, v17
	v_exp_f32_e32 v0, v0
	v_mov_b32_e32 v8, v1
	v_add_f32_e32 v0, 1.0, v0
	v_rcp_f32_e32 v0, v0
	s_nop 0
	v_mul_f32_e32 v0, v17, v0
	v_mul_f32_e32 v16, v16, v0
	v_mul_f32_e32 v0, 0xbfb8aa3b, v5
	v_exp_f32_e32 v0, v0
	s_nop 0
	v_add_f32_e32 v0, 1.0, v0
	v_rcp_f32_e32 v0, v0
	s_nop 0
	v_mul_f32_e32 v0, v5, v0
	v_mul_f32_e32 v4, v4, v0
	v_pk_mul_f32 v[0:1], v[8:9], v[64:65] op_sel_hi:[1,0]
	s_nop 0
	v_mul_f32_e32 v5, 0xbfb8aa3b, v1
	v_exp_f32_e32 v5, v5
	s_nop 0
	v_add_f32_e32 v5, 1.0, v5
	v_rcp_f32_e32 v5, v5
	s_nop 0
	v_mul_f32_e32 v1, v1, v5
	v_mul_f32_e32 v5, v0, v1
	v_mov_b32_e32 v0, v6
	v_mov_b32_e32 v1, v14
	v_pk_mul_f32 v[0:1], v[0:1], v[64:65] op_sel_hi:[1,0]
	v_mov_b32_e32 v14, v7
	v_mul_f32_e32 v6, 0xbfb8aa3b, v1
	v_exp_f32_e32 v6, v6
	s_nop 0
	v_add_f32_e32 v6, 1.0, v6
	v_rcp_f32_e32 v6, v6
	s_nop 0
	v_mul_f32_e32 v1, v1, v6
	v_mul_f32_e32 v6, v0, v1
	v_mov_b32_e32 v0, v2
	v_mov_b32_e32 v1, v10
	v_pk_mul_f32 v[0:1], v[0:1], v[64:65] op_sel_hi:[1,0]
	v_mov_b32_e32 v10, v3
	v_mul_f32_e32 v2, 0xbfb8aa3b, v1
	v_exp_f32_e32 v2, v2
	s_nop 0
	v_add_f32_e32 v2, 1.0, v2
	v_rcp_f32_e32 v2, v2
	s_nop 0
	v_mul_f32_e32 v1, v1, v2
	v_mul_f32_e32 v8, v0, v1
	v_pk_mul_f32 v[0:1], v[14:15], v[64:65] op_sel_hi:[1,0]
	s_nop 0
	v_mul_f32_e32 v2, 0xbfb8aa3b, v1
	v_exp_f32_e32 v2, v2
	s_nop 0
	v_add_f32_e32 v2, 1.0, v2
	v_rcp_f32_e32 v2, v2
	s_nop 0
	v_mul_f32_e32 v1, v1, v2
	v_mul_f32_e32 v2, v0, v1
	v_pk_mul_f32 v[0:1], v[10:11], v[64:65] op_sel_hi:[1,0]
	s_nop 0
	v_mul_f32_e32 v3, 0xbfb8aa3b, v1
	v_exp_f32_e32 v3, v3
	s_nop 0
	v_add_f32_e32 v3, 1.0, v3
	v_rcp_f32_e32 v3, v3
	s_nop 0
	v_mul_f32_e32 v1, v1, v3
	v_mul_f32_e32 v3, v0, v1
	v_cvt_pk_bf16_f32 v0, v18, v4
	v_cvt_pk_bf16_f32 v1, v6, v2
	v_cvt_pk_bf16_f32 v2, v16, v5
	v_mad_i64_i32 v[4:5], s[0:1], v158, s6, v[114:115]
	v_lshl_add_u64 v[4:5], v[4:5], 0, v[116:117]
	v_cvt_pk_bf16_f32 v3, v8, v3
	global_store_dwordx4 v[4:5], v[0:3], off sc1
	s_andn2_b64 vcc, exec, s[2:3]
	s_mov_b64 s[0:1], -1
	s_cbranch_vccnz .LBB0_300
	s_andn2_b64 vcc, exec, s[4:5]
	s_cbranch_vccnz .LBB0_299
	s_barrier
	s_branch .LBB0_299

; __device__ __forceinline__ float fsilu(float v) { return v * fsig(v); }
; __device__ __forceinline__ void rstd8(const float* ss, int row0, float sc, float (&rs)[2][4]) {
;     f32x4 pa[2][4];
; #pragma unroll
;     for (int ai = 0; ai < 2; ++ai)
; #pragma unroll
;         for (int m = 0; m < 4; ++m) pa[ai][m] = *(const f32x4*)(ss + (size_t)(row0 + ai * HALF + m * 16) * 4);
; #pragma unroll
;     for (int ai = 0; ai < 2; ++ai)
; #pragma unroll
;         for (int m = 0; m < 4; ++m) { const f32x4 a = pa[ai][m]; rs[ai][m] = rsqrtf(((a[0] + a[1]) + (a[2] + a[3])) * (1.0f / 1024.0f) + 1e-6f) * sc; }
;     __device__ __forceinline__ void operator()(const f32x4 (&acc)[2][2][4][2], const Unit& u, int wr, int wc, int fr, int fq) const {
;     ...
;             for (int m = 0; m < 4; ++m) { const int row = row0 + ai * HALF + m * 16; const float rs = rsv[ai][m];
;                 f32x4 o0, o1;
; #pragma unroll
;                 for (int i = 0; i < 4; ++i) { o0[i] = fsilu(acc[ai][0][m][0][i] * rs) * (acc[ai][1][m][0][i] * rs); o1[i] = fsilu(acc[ai][0][m][1][i] * rs) * (acc[ai][1][m][1][i] * rs); }
.LBB0_1453:
	v_lshl_add_u32 v178, s0, 8, v171
	v_ashrrev_i32_e32 v179, 31, v178
	v_or_b32_e32 v172, 16, v178
	v_lshl_add_u64 v[130:131], v[178:179], 4, s[4:5]
	v_ashrrev_i32_e32 v173, 31, v172
	global_load_dwordx4 v[184:187], v[130:131], off
	v_lshl_add_u64 v[130:131], v[172:173], 4, s[4:5]
	global_load_dwordx4 v[188:191], v[130:131], off
	v_or_b32_e32 v168, 32, v178
	v_ashrrev_i32_e32 v169, 31, v168
	v_or_b32_e32 v166, 48, v178
	v_lshl_add_u64 v[130:131], v[168:169], 4, s[4:5]
	v_ashrrev_i32_e32 v167, 31, v166
	global_load_dwordx4 v[192:195], v[130:131], off
	v_lshl_add_u64 v[130:131], v[166:167], 4, s[4:5]
	global_load_dwordx4 v[210:213], v[130:131], off
	v_add_u32_e32 v164, 0x80, v178
	v_ashrrev_i32_e32 v165, 31, v164
	v_add_u32_e32 v162, 0x90, v178
	v_lshl_add_u64 v[130:131], v[164:165], 4, s[4:5]
	v_ashrrev_i32_e32 v163, 31, v162
	global_load_dwordx4 v[142:145], v[130:131], off
	v_lshl_add_u64 v[130:131], v[162:163], 4, s[4:5]
	global_load_dwordx4 v[138:141], v[130:131], off
	v_add_u32_e32 v160, 0xa0, v178
	v_ashrrev_i32_e32 v161, 31, v160
	v_add_u32_e32 v158, 0xb0, v178
	v_lshl_add_u64 v[130:131], v[160:161], 4, s[4:5]
	v_ashrrev_i32_e32 v159, 31, v158
	global_load_dwordx4 v[134:137], v[130:131], off
	v_lshl_add_u64 v[130:131], v[158:159], 4, s[4:5]
	global_load_dwordx4 v[130:133], v[130:131], off
	v_lshl_or_b32 v180, s1, 7, v177
	s_waitcnt vmcnt(0)
	v_mov_b32_e32 v214, v185
	v_mov_b32_e32 v215, v186
	v_mov_b32_e32 v185, v187
	v_mov_b32_e32 v186, v189
	v_mov_b32_e32 v187, v190
	v_mov_b32_e32 v189, v191
	v_pk_add_f32 v[184:185], v[214:215], v[184:185]
	v_pk_add_f32 v[186:187], v[186:187], v[188:189]
	v_mov_b32_e32 v189, v184
	v_mov_b32_e32 v188, v186
	v_mov_b32_e32 v184, v187
	v_pk_add_f32 v[186:187], v[188:189], v[184:185]
	v_mov_b64_e32 v[184:185], s[52:53]
	v_pk_fma_f32 v[186:187], v[186:187], s[42:43], v[184:185] op_sel_hi:[1,0,0]
	v_mov_b32_e32 v188, v211
	v_mul_f32_e32 v64, 0x4b800000, v187
	v_cmp_gt_f32_e64 s[0:1], s28, v187
	v_cmp_gt_f32_e32 vcc, s28, v186
	v_mov_b32_e32 v189, v212
	v_cndmask_b32_e64 v64, v187, v64, s[0:1]
	v_rsq_f32_e32 v64, v64
	v_mov_b32_e32 v187, v194
	v_mov_b32_e32 v211, v213
	v_pk_add_f32 v[188:189], v[188:189], v[210:211]
	v_mul_f32_e32 v159, 0x45800000, v64
	v_cndmask_b32_e64 v182, v64, v159, s[0:1]
	v_mul_f32_e32 v64, 0x4b800000, v186
	v_cndmask_b32_e32 v64, v186, v64, vcc
	v_rsq_f32_e32 v64, v64
	v_mov_b32_e32 v186, v193
	v_mov_b32_e32 v193, v195
	v_pk_add_f32 v[186:187], v[186:187], v[192:193]
	v_mov_b32_e32 v190, v188
	v_mov_b32_e32 v191, v186
	v_mov_b32_e32 v186, v189
	v_pk_add_f32 v[186:187], v[190:191], v[186:187]
	v_mul_f32_e32 v159, 0x45800000, v64
	v_pk_fma_f32 v[186:187], v[186:187], s[42:43], v[184:185] op_sel_hi:[1,0,0]
	v_cndmask_b32_e32 v176, v64, v159, vcc
	v_mul_f32_e32 v64, 0x4b800000, v187
	v_cmp_gt_f32_e64 s[0:1], s28, v187
	v_cmp_gt_f32_e32 vcc, s28, v186
	s_nop 0
	v_cndmask_b32_e64 v64, v187, v64, s[0:1]
	v_rsq_f32_e32 v64, v64
	v_mov_b32_e32 v187, v144
	v_mov_b32_e32 v144, v139
	v_mov_b32_e32 v139, v141
	v_mul_f32_e32 v159, 0x45800000, v64
	v_cndmask_b32_e64 v174, v64, v159, s[0:1]
	v_mul_f32_e32 v64, 0x4b800000, v186
	v_cndmask_b32_e32 v64, v186, v64, vcc
	v_rsq_f32_e32 v64, v64
	v_mov_b32_e32 v186, v143
	v_mov_b32_e32 v143, v145
	v_mov_b32_e32 v145, v140
	v_pk_add_f32 v[142:143], v[186:187], v[142:143]
	v_pk_add_f32 v[138:139], v[144:145], v[138:139]
	v_mov_b32_e32 v141, v142
	v_mov_b32_e32 v140, v138
	v_mov_b32_e32 v142, v139
	v_pk_add_f32 v[138:139], v[140:141], v[142:143]
	v_mul_f32_e32 v159, 0x45800000, v64
	v_pk_fma_f32 v[138:139], v[138:139], s[42:43], v[184:185] op_sel_hi:[1,0,0]
	v_cndmask_b32_e32 v170, v64, v159, vcc
	v_mul_f32_e32 v64, 0x4b800000, v139
	v_cmp_gt_f32_e64 s[0:1], s28, v139
	v_cmp_gt_f32_e32 vcc, s28, v138
	v_mov_b32_e32 v142, v135
	v_cndmask_b32_e64 v64, v139, v64, s[0:1]
	v_rsq_f32_e32 v64, v64
	v_mov_b32_e32 v143, v136
	v_mov_b32_e32 v135, v137
	v_mov_b32_e32 v136, v131
	v_mul_f32_e32 v139, 0x45800000, v64
	v_cndmask_b32_e64 v140, v64, v139, s[0:1]
	v_mul_f32_e32 v64, 0x4b800000, v138
	v_cndmask_b32_e32 v64, v138, v64, vcc
	v_rsq_f32_e32 v64, v64
	v_mov_b32_e32 v137, v132
	v_mov_b32_e32 v131, v133
	v_pk_add_f32 v[134:135], v[142:143], v[134:135]
	v_pk_add_f32 v[130:131], v[136:137], v[130:131]
	v_mov_b32_e32 v133, v134
	v_mov_b32_e32 v132, v130
	v_mov_b32_e32 v134, v131
	v_pk_add_f32 v[130:131], v[132:133], v[134:135]
	v_mul_f32_e32 v138, 0x45800000, v64
	v_pk_fma_f32 v[132:133], v[130:131], s[42:43], v[184:185] op_sel_hi:[1,0,0]
	v_cndmask_b32_e32 v138, v64, v138, vcc
	v_mul_f32_e32 v64, 0x4b800000, v133
	v_cmp_gt_f32_e64 s[0:1], s28, v133
	v_cmp_gt_f32_e32 vcc, s28, v132
	s_nop 0
	v_cndmask_b32_e64 v64, v133, v64, s[0:1]
	v_rsq_f32_e32 v64, v64
	s_nop 0
	v_mul_f32_e32 v130, 0x45800000, v64
	v_cndmask_b32_e64 v130, v64, v130, s[0:1]
	v_mul_f32_e32 v64, 0x4b800000, v132
	v_cndmask_b32_e32 v64, v132, v64, vcc
	v_rsq_f32_e32 v64, v64
	s_nop 0
	v_mul_f32_e32 v131, 0x45800000, v64
	v_cndmask_b32_e32 v64, v64, v131, vcc
	v_mov_b32_e32 v132, v118
	v_mov_b32_e32 v133, v126
	v_pk_mul_f32 v[132:133], v[132:133], v[182:183] op_sel_hi:[1,0]
	v_mov_b32_e32 v126, v119
	v_mul_f32_e32 v118, 0xbfb8aa3b, v133
	v_exp_f32_e32 v118, v118
	v_readlane_b32 s0, v254, 9
	v_readlane_b32 s1, v254, 10
	v_ashrrev_i32_e32 v181, 31, v180
	v_add_f32_e32 v118, 1.0, v118
	v_rcp_f32_e32 v118, v118
	s_movk_i32 s11, 0x1600
	v_mul_f32_e32 v118, v133, v118
	v_mul_f32_e32 v131, v132, v118
	v_mov_b32_e32 v132, v114
	v_mov_b32_e32 v133, v122
	v_pk_mul_f32 v[132:133], v[132:133], v[182:183] op_sel_hi:[1,0]
	v_pk_mul_f32 v[118:119], v[126:127], v[182:183] op_sel_hi:[1,0]
; __device__ __forceinline__ u32x4 pack8(const f32x4 v0, const f32x4 v1) { u32x4 w; w.x = cvt_pk_bf16(v0[0], v0[1]); w.y = cvt_pk_bf16(v0[2], v0[3]); w.z = cvt_pk_bf16(v1[0], v1[1]); w.w = cvt_pk_bf16(v1[2], v1[3]); return w; }
; __device__ __forceinline__ float fsig(float v) { return __builtin_amdgcn_rcpf(1.f + __expf(-v)); }
; __device__ __forceinline__ float fsilu(float v) { return v * fsig(v); }
;     __device__ __forceinline__ void operator()(const f32x4 (&acc)[2][2][4][2], const Unit& u, int wr, int wc, int fr, int fq) const {
;     ...
;             for (int m = 0; m < 4; ++m) { const int row = row0 + ai * HALF + m * 16; const float rs = rsv[ai][m];
;                 f32x4 o0, o1;
; #pragma unroll
;                 for (int i = 0; i < 4; ++i) { o0[i] = fsilu(acc[ai][0][m][0][i] * rs) * (acc[ai][1][m][0][i] * rs); o1[i] = fsilu(acc[ai][0][m][1][i] * rs) * (acc[ai][1][m][1][i] * rs); }
;                 *(u32x4*)(H + (size_t)row * ldh + col0) = pack8(o0, o1); __builtin_amdgcn_sched_barrier(0); }
	v_mul_f32_e32 v114, 0xbfb8aa3b, v133
	v_exp_f32_e32 v114, v114
	v_mov_b32_e32 v122, v115
	v_add_f32_e32 v114, 1.0, v114
	v_rcp_f32_e32 v114, v114
	s_nop 0
	v_mul_f32_e32 v114, v133, v114
	v_mul_f32_e32 v132, v132, v114
	v_mul_f32_e32 v114, 0xbfb8aa3b, v119
	v_exp_f32_e32 v114, v114
	s_nop 0
	v_add_f32_e32 v114, 1.0, v114
	v_rcp_f32_e32 v114, v114
	s_nop 0
	v_mul_f32_e32 v114, v119, v114
	v_mul_f32_e32 v118, v118, v114
	v_pk_mul_f32 v[114:115], v[122:123], v[182:183] op_sel_hi:[1,0]
	v_cvt_pk_bf16_f32 v118, v131, v118
	s_nop 0
	v_mul_f32_e32 v119, 0xbfb8aa3b, v115
	v_exp_f32_e32 v119, v119
	s_nop 0
	v_add_f32_e32 v119, 1.0, v119
	v_rcp_f32_e32 v119, v119
	s_nop 0
	v_mul_f32_e32 v115, v115, v119
	v_mul_f32_e32 v122, v114, v115
	v_mov_b32_e32 v114, v120
	v_mov_b32_e32 v115, v128
	v_pk_mul_f32 v[114:115], v[114:115], v[182:183] op_sel_hi:[1,0]
	v_mov_b32_e32 v128, v121
	v_mul_f32_e32 v119, 0xbfb8aa3b, v115
	v_exp_f32_e32 v119, v119
	s_nop 0
	v_add_f32_e32 v119, 1.0, v119
	v_rcp_f32_e32 v119, v119
	s_nop 0
	v_mul_f32_e32 v115, v115, v119
	v_mul_f32_e32 v119, v114, v115
	v_mov_b32_e32 v114, v116
	v_mov_b32_e32 v115, v124
	v_pk_mul_f32 v[114:115], v[114:115], v[182:183] op_sel_hi:[1,0]
	v_mov_b32_e32 v124, v117
	v_mul_f32_e32 v116, 0xbfb8aa3b, v115
	v_exp_f32_e32 v116, v116
	s_nop 0
	v_add_f32_e32 v116, 1.0, v116
	v_rcp_f32_e32 v116, v116
	s_nop 0
	v_mul_f32_e32 v115, v115, v116
	v_mul_f32_e32 v116, v114, v115
	v_pk_mul_f32 v[114:115], v[128:129], v[182:183] op_sel_hi:[1,0]
	s_nop 0
	v_mul_f32_e32 v120, 0xbfb8aa3b, v115
	v_exp_f32_e32 v120, v120
	s_nop 0
	v_add_f32_e32 v120, 1.0, v120
	v_rcp_f32_e32 v120, v120
	s_nop 0
	v_mul_f32_e32 v115, v115, v120
	v_mul_f32_e32 v120, v114, v115
	v_pk_mul_f32 v[114:115], v[124:125], v[182:183] op_sel_hi:[1,0]
	v_cvt_pk_bf16_f32 v119, v119, v120
	v_cvt_pk_bf16_f32 v120, v132, v122
	s_nop 0
	v_mul_f32_e32 v117, 0xbfb8aa3b, v115
	v_exp_f32_e32 v117, v117
	s_nop 0
	v_add_f32_e32 v117, 1.0, v117
	v_rcp_f32_e32 v117, v117
	s_nop 0
	v_mul_f32_e32 v115, v115, v117
	v_mul_f32_e32 v114, v114, v115
	v_cvt_pk_bf16_f32 v121, v116, v114
	v_mov_b64_e32 v[114:115], s[0:1]
	v_mad_i64_i32 v[122:123], s[0:1], v178, s11, v[114:115]
	v_lshlrev_b64 v[116:117], 1, v[180:181]
	v_lshl_add_u64 v[122:123], v[122:123], 0, v[116:117]
	global_store_dwordx4 v[122:123], v[118:121], off sc1
	s_nop 1
	v_mov_b32_e32 v118, v102
	v_mov_b32_e32 v119, v110
	v_pk_mul_f32 v[118:119], v[118:119], v[176:177] op_sel_hi:[1,0]
	v_mov_b32_e32 v110, v103
	v_mul_f32_e32 v102, 0xbfb8aa3b, v119
	v_exp_f32_e32 v102, v102
	s_nop 0
	v_add_f32_e32 v102, 1.0, v102
	v_rcp_f32_e32 v102, v102
	s_nop 0
	v_mul_f32_e32 v102, v119, v102
	v_mul_f32_e32 v120, v118, v102
	v_mov_b32_e32 v118, v98
	v_mov_b32_e32 v119, v106
	v_pk_mul_f32 v[118:119], v[118:119], v[176:177] op_sel_hi:[1,0]
	v_pk_mul_f32 v[102:103], v[110:111], v[176:177] op_sel_hi:[1,0]
	v_mul_f32_e32 v98, 0xbfb8aa3b, v119
	v_exp_f32_e32 v98, v98
	v_mov_b32_e32 v106, v99
	v_add_f32_e32 v98, 1.0, v98
	v_rcp_f32_e32 v98, v98
	s_nop 0
	v_mul_f32_e32 v98, v119, v98
	v_mul_f32_e32 v118, v118, v98
	v_mul_f32_e32 v98, 0xbfb8aa3b, v103
	v_exp_f32_e32 v98, v98
	s_nop 0
	v_add_f32_e32 v98, 1.0, v98
	v_rcp_f32_e32 v98, v98
	s_nop 0
	v_mul_f32_e32 v98, v103, v98
	v_mul_f32_e32 v102, v102, v98
	v_pk_mul_f32 v[98:99], v[106:107], v[176:177] op_sel_hi:[1,0]
	s_nop 0
	v_mul_f32_e32 v103, 0xbfb8aa3b, v99
	v_exp_f32_e32 v103, v103
	s_nop 0
	v_add_f32_e32 v103, 1.0, v103
	v_rcp_f32_e32 v103, v103
	s_nop 0
	v_mul_f32_e32 v99, v99, v103
	v_mul_f32_e32 v103, v98, v99
	v_mov_b32_e32 v98, v104
	v_mov_b32_e32 v99, v112
	v_pk_mul_f32 v[98:99], v[98:99], v[176:177] op_sel_hi:[1,0]
	v_mov_b32_e32 v112, v105
	v_mul_f32_e32 v104, 0xbfb8aa3b, v99
	v_exp_f32_e32 v104, v104
	s_nop 0
	v_add_f32_e32 v104, 1.0, v104
	v_rcp_f32_e32 v104, v104
	s_nop 0
	v_mul_f32_e32 v99, v99, v104
	v_mul_f32_e32 v104, v98, v99
	v_mov_b32_e32 v98, v100
	v_mov_b32_e32 v99, v108
	v_pk_mul_f32 v[98:99], v[98:99], v[176:177] op_sel_hi:[1,0]
	v_mov_b32_e32 v108, v101
	v_mul_f32_e32 v100, 0xbfb8aa3b, v99
	v_exp_f32_e32 v100, v100
	s_nop 0
	v_add_f32_e32 v100, 1.0, v100
	v_rcp_f32_e32 v100, v100
	s_nop 0
	v_mul_f32_e32 v99, v99, v100
	v_mul_f32_e32 v106, v98, v99
	v_pk_mul_f32 v[98:99], v[112:113], v[176:177] op_sel_hi:[1,0]
	s_nop 0
	v_mul_f32_e32 v100, 0xbfb8aa3b, v99
	v_exp_f32_e32 v100, v100
	s_nop 0
	v_add_f32_e32 v100, 1.0, v100
	v_rcp_f32_e32 v100, v100
	s_nop 0
	v_mul_f32_e32 v99, v99, v100
	v_mul_f32_e32 v100, v98, v99
	v_pk_mul_f32 v[98:99], v[108:109], v[176:177] op_sel_hi:[1,0]
	s_nop 0
	v_mul_f32_e32 v101, 0xbfb8aa3b, v99
	v_exp_f32_e32 v101, v101
	s_nop 0
	v_add_f32_e32 v101, 1.0, v101
	v_rcp_f32_e32 v101, v101
	s_nop 0
	v_mul_f32_e32 v99, v99, v101
	v_mul_f32_e32 v101, v98, v99
	v_cvt_pk_bf16_f32 v98, v120, v102
	v_cvt_pk_bf16_f32 v99, v104, v100
	v_cvt_pk_bf16_f32 v100, v118, v103
	v_mad_i64_i32 v[102:103], s[0:1], v172, s11, v[114:115]
	v_lshl_add_u64 v[102:103], v[102:103], 0, v[116:117]
	v_cvt_pk_bf16_f32 v101, v106, v101
	global_store_dwordx4 v[102:103], v[98:101], off sc1
	s_nop 1
	v_mov_b32_e32 v98, v86
	v_mov_b32_e32 v99, v94
	v_pk_mul_f32 v[98:99], v[98:99], v[174:175] op_sel_hi:[1,0]
	v_mov_b32_e32 v94, v87
	v_mul_f32_e32 v86, 0xbfb8aa3b, v99
	v_exp_f32_e32 v86, v86
	s_nop 0
	v_add_f32_e32 v86, 1.0, v86
	v_rcp_f32_e32 v86, v86
	s_nop 0
	v_mul_f32_e32 v86, v99, v86
	v_mul_f32_e32 v100, v98, v86
	v_mov_b32_e32 v98, v82
	v_mov_b32_e32 v99, v90
	v_pk_mul_f32 v[98:99], v[98:99], v[174:175] op_sel_hi:[1,0]
	v_pk_mul_f32 v[86:87], v[94:95], v[174:175] op_sel_hi:[1,0]
	v_mul_f32_e32 v82, 0xbfb8aa3b, v99
	v_exp_f32_e32 v82, v82
	v_mov_b32_e32 v90, v83
; __device__ __forceinline__ u32x4 pack8(const f32x4 v0, const f32x4 v1) { u32x4 w; w.x = cvt_pk_bf16(v0[0], v0[1]); w.y = cvt_pk_bf16(v0[2], v0[3]); w.z = cvt_pk_bf16(v1[0], v1[1]); w.w = cvt_pk_bf16(v1[2], v1[3]); return w; }
; __device__ __forceinline__ float fsig(float v) { return __builtin_amdgcn_rcpf(1.f + __expf(-v)); }
; __device__ __forceinline__ float fsilu(float v) { return v * fsig(v); }
;     __device__ __forceinline__ void operator()(const f32x4 (&acc)[2][2][4][2], const Unit& u, int wr, int wc, int fr, int fq) const {
;     ...
;             for (int m = 0; m < 4; ++m) { const int row = row0 + ai * HALF + m * 16; const float rs = rsv[ai][m];
;                 f32x4 o0, o1;
; #pragma unroll
;                 for (int i = 0; i < 4; ++i) { o0[i] = fsilu(acc[ai][0][m][0][i] * rs) * (acc[ai][1][m][0][i] * rs); o1[i] = fsilu(acc[ai][0][m][1][i] * rs) * (acc[ai][1][m][1][i] * rs); }
;                 *(u32x4*)(H + (size_t)row * ldh + col0) = pack8(o0, o1); __builtin_amdgcn_sched_barrier(0); }
	v_add_f32_e32 v82, 1.0, v82
	v_rcp_f32_e32 v82, v82
	s_nop 0
	v_mul_f32_e32 v82, v99, v82
	v_mul_f32_e32 v98, v98, v82
	v_mul_f32_e32 v82, 0xbfb8aa3b, v87
	v_exp_f32_e32 v82, v82
	s_nop 0
	v_add_f32_e32 v82, 1.0, v82
	v_rcp_f32_e32 v82, v82
	s_nop 0
	v_mul_f32_e32 v82, v87, v82
	v_mul_f32_e32 v86, v86, v82
	v_pk_mul_f32 v[82:83], v[90:91], v[174:175] op_sel_hi:[1,0]
	s_nop 0
	v_mul_f32_e32 v87, 0xbfb8aa3b, v83
	v_exp_f32_e32 v87, v87
	s_nop 0
	v_add_f32_e32 v87, 1.0, v87
	v_rcp_f32_e32 v87, v87
	s_nop 0
	v_mul_f32_e32 v83, v83, v87
	v_mul_f32_e32 v87, v82, v83
	v_mov_b32_e32 v82, v88
	v_mov_b32_e32 v83, v96
	v_pk_mul_f32 v[82:83], v[82:83], v[174:175] op_sel_hi:[1,0]
	v_mov_b32_e32 v96, v89
	v_mul_f32_e32 v88, 0xbfb8aa3b, v83
	v_exp_f32_e32 v88, v88
	s_nop 0
	v_add_f32_e32 v88, 1.0, v88
	v_rcp_f32_e32 v88, v88
	s_nop 0
	v_mul_f32_e32 v83, v83, v88
	v_mul_f32_e32 v88, v82, v83
	v_mov_b32_e32 v82, v84
	v_mov_b32_e32 v83, v92
	v_pk_mul_f32 v[82:83], v[82:83], v[174:175] op_sel_hi:[1,0]
	v_mov_b32_e32 v92, v85
	v_mul_f32_e32 v84, 0xbfb8aa3b, v83
	v_exp_f32_e32 v84, v84
	s_nop 0
	v_add_f32_e32 v84, 1.0, v84
	v_rcp_f32_e32 v84, v84
	s_nop 0
	v_mul_f32_e32 v83, v83, v84
	v_mul_f32_e32 v90, v82, v83
	v_pk_mul_f32 v[82:83], v[96:97], v[174:175] op_sel_hi:[1,0]
	s_nop 0
	v_mul_f32_e32 v84, 0xbfb8aa3b, v83
	v_exp_f32_e32 v84, v84
	s_nop 0
	v_add_f32_e32 v84, 1.0, v84
	v_rcp_f32_e32 v84, v84
	s_nop 0
	v_mul_f32_e32 v83, v83, v84
	v_mul_f32_e32 v84, v82, v83
	v_pk_mul_f32 v[82:83], v[92:93], v[174:175] op_sel_hi:[1,0]
	s_nop 0
	v_mul_f32_e32 v85, 0xbfb8aa3b, v83
	v_exp_f32_e32 v85, v85
	s_nop 0
	v_add_f32_e32 v85, 1.0, v85
	v_rcp_f32_e32 v85, v85
	s_nop 0
	v_mul_f32_e32 v83, v83, v85
	v_mul_f32_e32 v85, v82, v83
	v_cvt_pk_bf16_f32 v82, v100, v86
	v_cvt_pk_bf16_f32 v83, v88, v84
	v_cvt_pk_bf16_f32 v84, v98, v87
	v_mad_i64_i32 v[86:87], s[0:1], v168, s11, v[114:115]
	v_lshl_add_u64 v[86:87], v[86:87], 0, v[116:117]
	v_cvt_pk_bf16_f32 v85, v90, v85
	global_store_dwordx4 v[86:87], v[82:85], off sc1
	s_nop 1
	v_mov_b32_e32 v82, v70
	v_mov_b32_e32 v83, v78
	v_pk_mul_f32 v[82:83], v[82:83], v[170:171] op_sel_hi:[1,0]
	v_mov_b32_e32 v78, v71
	v_mul_f32_e32 v70, 0xbfb8aa3b, v83
	v_exp_f32_e32 v70, v70
	s_nop 0
	v_add_f32_e32 v70, 1.0, v70
	v_rcp_f32_e32 v70, v70
	s_nop 0
	v_mul_f32_e32 v70, v83, v70
	v_mul_f32_e32 v84, v82, v70
	v_mov_b32_e32 v82, v66
	v_mov_b32_e32 v83, v74
	v_pk_mul_f32 v[82:83], v[82:83], v[170:171] op_sel_hi:[1,0]
	v_pk_mul_f32 v[70:71], v[78:79], v[170:171] op_sel_hi:[1,0]
	v_mul_f32_e32 v66, 0xbfb8aa3b, v83
	v_exp_f32_e32 v66, v66
	v_mov_b32_e32 v74, v67
	v_add_f32_e32 v66, 1.0, v66
	v_rcp_f32_e32 v66, v66
	s_nop 0
	v_mul_f32_e32 v66, v83, v66
	v_mul_f32_e32 v82, v82, v66
	v_mul_f32_e32 v66, 0xbfb8aa3b, v71
	v_exp_f32_e32 v66, v66
	s_nop 0
	v_add_f32_e32 v66, 1.0, v66
	v_rcp_f32_e32 v66, v66
	s_nop 0
	v_mul_f32_e32 v66, v71, v66
	v_mul_f32_e32 v70, v70, v66
	v_pk_mul_f32 v[66:67], v[74:75], v[170:171] op_sel_hi:[1,0]
	s_nop 0
	v_mul_f32_e32 v71, 0xbfb8aa3b, v67
	v_exp_f32_e32 v71, v71
	s_nop 0
	v_add_f32_e32 v71, 1.0, v71
	v_rcp_f32_e32 v71, v71
	s_nop 0
	v_mul_f32_e32 v67, v67, v71
	v_mul_f32_e32 v71, v66, v67
	v_mov_b32_e32 v66, v72
	v_mov_b32_e32 v67, v80
	v_pk_mul_f32 v[66:67], v[66:67], v[170:171] op_sel_hi:[1,0]
	v_mov_b32_e32 v80, v73
	v_mul_f32_e32 v72, 0xbfb8aa3b, v67
	v_exp_f32_e32 v72, v72
	s_nop 0
	v_add_f32_e32 v72, 1.0, v72
	v_rcp_f32_e32 v72, v72
	s_nop 0
	v_mul_f32_e32 v67, v67, v72
	v_mul_f32_e32 v72, v66, v67
	v_mov_b32_e32 v66, v68
	v_mov_b32_e32 v67, v76
	v_pk_mul_f32 v[66:67], v[66:67], v[170:171] op_sel_hi:[1,0]
	v_mov_b32_e32 v76, v69
	v_mul_f32_e32 v68, 0xbfb8aa3b, v67
	v_exp_f32_e32 v68, v68
	s_nop 0
	v_add_f32_e32 v68, 1.0, v68
	v_rcp_f32_e32 v68, v68
	s_nop 0
	v_mul_f32_e32 v67, v67, v68
	v_mul_f32_e32 v74, v66, v67
	v_pk_mul_f32 v[66:67], v[80:81], v[170:171] op_sel_hi:[1,0]
	s_nop 0
	v_mul_f32_e32 v68, 0xbfb8aa3b, v67
	v_exp_f32_e32 v68, v68
	s_nop 0
	v_add_f32_e32 v68, 1.0, v68
	v_rcp_f32_e32 v68, v68
	s_nop 0
	v_mul_f32_e32 v67, v67, v68
	v_mul_f32_e32 v68, v66, v67
	v_pk_mul_f32 v[66:67], v[76:77], v[170:171] op_sel_hi:[1,0]
	s_nop 0
	v_mul_f32_e32 v69, 0xbfb8aa3b, v67
	v_exp_f32_e32 v69, v69
	s_nop 0
	v_add_f32_e32 v69, 1.0, v69
	v_rcp_f32_e32 v69, v69
	s_nop 0
	v_mul_f32_e32 v67, v67, v69
	v_mul_f32_e32 v69, v66, v67
	v_cvt_pk_bf16_f32 v66, v84, v70
	v_cvt_pk_bf16_f32 v67, v72, v68
	v_cvt_pk_bf16_f32 v68, v82, v71
	v_mad_i64_i32 v[70:71], s[0:1], v166, s11, v[114:115]
	v_lshl_add_u64 v[70:71], v[70:71], 0, v[116:117]
	v_cvt_pk_bf16_f32 v69, v74, v69
	global_store_dwordx4 v[70:71], v[66:69], off sc1
	s_nop 1
	v_mov_b32_e32 v66, v52
	v_mov_b32_e32 v67, v60
	v_pk_mul_f32 v[66:67], v[66:67], v[140:141] op_sel_hi:[1,0]
	v_mov_b32_e32 v60, v53
	v_mul_f32_e32 v52, 0xbfb8aa3b, v67
	v_exp_f32_e32 v52, v52
	s_nop 0
	v_add_f32_e32 v52, 1.0, v52
	v_rcp_f32_e32 v52, v52
	s_nop 0
	v_mul_f32_e32 v52, v67, v52
	v_mul_f32_e32 v68, v66, v52
	v_mov_b32_e32 v66, v48
	v_mov_b32_e32 v67, v56
	v_pk_mul_f32 v[66:67], v[66:67], v[140:141] op_sel_hi:[1,0]
	v_pk_mul_f32 v[52:53], v[60:61], v[140:141] op_sel_hi:[1,0]
	v_mul_f32_e32 v48, 0xbfb8aa3b, v67
	v_exp_f32_e32 v48, v48
	v_mov_b32_e32 v56, v49
	v_add_f32_e32 v48, 1.0, v48
	v_rcp_f32_e32 v48, v48
	s_nop 0
	v_mul_f32_e32 v48, v67, v48
	v_mul_f32_e32 v66, v66, v48
	v_mul_f32_e32 v48, 0xbfb8aa3b, v53
	v_exp_f32_e32 v48, v48
	s_nop 0
	v_add_f32_e32 v48, 1.0, v48
	v_rcp_f32_e32 v48, v48
	s_nop 0
	v_mul_f32_e32 v48, v53, v48
	v_mul_f32_e32 v52, v52, v48
	v_pk_mul_f32 v[48:49], v[56:57], v[140:141] op_sel_hi:[1,0]
	s_nop 0
	v_mul_f32_e32 v53, 0xbfb8aa3b, v49
	v_exp_f32_e32 v53, v53
; __device__ __forceinline__ u32x4 pack8(const f32x4 v0, const f32x4 v1) { u32x4 w; w.x = cvt_pk_bf16(v0[0], v0[1]); w.y = cvt_pk_bf16(v0[2], v0[3]); w.z = cvt_pk_bf16(v1[0], v1[1]); w.w = cvt_pk_bf16(v1[2], v1[3]); return w; }
; __device__ __forceinline__ float fsig(float v) { return __builtin_amdgcn_rcpf(1.f + __expf(-v)); }
; __device__ __forceinline__ float fsilu(float v) { return v * fsig(v); }
;     __device__ __forceinline__ void operator()(const f32x4 (&acc)[2][2][4][2], const Unit& u, int wr, int wc, int fr, int fq) const {
;     ...
;             for (int m = 0; m < 4; ++m) { const int row = row0 + ai * HALF + m * 16; const float rs = rsv[ai][m];
;                 f32x4 o0, o1;
; #pragma unroll
;                 for (int i = 0; i < 4; ++i) { o0[i] = fsilu(acc[ai][0][m][0][i] * rs) * (acc[ai][1][m][0][i] * rs); o1[i] = fsilu(acc[ai][0][m][1][i] * rs) * (acc[ai][1][m][1][i] * rs); }
;                 *(u32x4*)(H + (size_t)row * ldh + col0) = pack8(o0, o1); __builtin_amdgcn_sched_barrier(0); }
	s_nop 0
	v_add_f32_e32 v53, 1.0, v53
	v_rcp_f32_e32 v53, v53
	s_nop 0
	v_mul_f32_e32 v49, v49, v53
	v_mul_f32_e32 v53, v48, v49
	v_mov_b32_e32 v48, v54
	v_mov_b32_e32 v49, v62
	v_pk_mul_f32 v[48:49], v[48:49], v[140:141] op_sel_hi:[1,0]
	v_mov_b32_e32 v62, v55
	v_mul_f32_e32 v54, 0xbfb8aa3b, v49
	v_exp_f32_e32 v54, v54
	s_nop 0
	v_add_f32_e32 v54, 1.0, v54
	v_rcp_f32_e32 v54, v54
	s_nop 0
	v_mul_f32_e32 v49, v49, v54
	v_mul_f32_e32 v54, v48, v49
	v_mov_b32_e32 v48, v50
	v_mov_b32_e32 v49, v58
	v_pk_mul_f32 v[48:49], v[48:49], v[140:141] op_sel_hi:[1,0]
	v_mov_b32_e32 v58, v51
	v_mul_f32_e32 v50, 0xbfb8aa3b, v49
	v_exp_f32_e32 v50, v50
	s_nop 0
	v_add_f32_e32 v50, 1.0, v50
	v_rcp_f32_e32 v50, v50
	s_nop 0
	v_mul_f32_e32 v49, v49, v50
	v_mul_f32_e32 v56, v48, v49
	v_pk_mul_f32 v[48:49], v[62:63], v[140:141] op_sel_hi:[1,0]
	s_nop 0
	v_mul_f32_e32 v50, 0xbfb8aa3b, v49
	v_exp_f32_e32 v50, v50
	s_nop 0
	v_add_f32_e32 v50, 1.0, v50
	v_rcp_f32_e32 v50, v50
	s_nop 0
	v_mul_f32_e32 v49, v49, v50
	v_mul_f32_e32 v50, v48, v49
	v_pk_mul_f32 v[48:49], v[58:59], v[140:141] op_sel_hi:[1,0]
	s_nop 0
	v_mul_f32_e32 v51, 0xbfb8aa3b, v49
	v_exp_f32_e32 v51, v51
	s_nop 0
	v_add_f32_e32 v51, 1.0, v51
	v_rcp_f32_e32 v51, v51
	s_nop 0
	v_mul_f32_e32 v49, v49, v51
	v_mul_f32_e32 v51, v48, v49
	v_cvt_pk_bf16_f32 v48, v68, v52
	v_cvt_pk_bf16_f32 v49, v54, v50
	v_cvt_pk_bf16_f32 v50, v66, v53
	v_mad_i64_i32 v[52:53], s[0:1], v164, s11, v[114:115]
	v_lshl_add_u64 v[52:53], v[52:53], 0, v[116:117]
	v_cvt_pk_bf16_f32 v51, v56, v51
	global_store_dwordx4 v[52:53], v[48:51], off sc1
	s_nop 1
	v_mov_b32_e32 v48, v36
	v_mov_b32_e32 v49, v44
	v_pk_mul_f32 v[48:49], v[48:49], v[138:139] op_sel_hi:[1,0]
	v_mov_b32_e32 v44, v37
	v_mul_f32_e32 v36, 0xbfb8aa3b, v49
	v_exp_f32_e32 v36, v36
	s_nop 0
	v_add_f32_e32 v36, 1.0, v36
	v_rcp_f32_e32 v36, v36
	s_nop 0
	v_mul_f32_e32 v36, v49, v36
	v_mul_f32_e32 v50, v48, v36
	v_mov_b32_e32 v48, v32
	v_mov_b32_e32 v49, v40
	v_pk_mul_f32 v[48:49], v[48:49], v[138:139] op_sel_hi:[1,0]
	v_pk_mul_f32 v[36:37], v[44:45], v[138:139] op_sel_hi:[1,0]
	v_mul_f32_e32 v32, 0xbfb8aa3b, v49
	v_exp_f32_e32 v32, v32
	v_mov_b32_e32 v40, v33
	v_add_f32_e32 v32, 1.0, v32
	v_rcp_f32_e32 v32, v32
	s_nop 0
	v_mul_f32_e32 v32, v49, v32
	v_mul_f32_e32 v48, v48, v32
	v_mul_f32_e32 v32, 0xbfb8aa3b, v37
	v_exp_f32_e32 v32, v32
	s_nop 0
	v_add_f32_e32 v32, 1.0, v32
	v_rcp_f32_e32 v32, v32
	s_nop 0
	v_mul_f32_e32 v32, v37, v32
	v_mul_f32_e32 v36, v36, v32
	v_pk_mul_f32 v[32:33], v[40:41], v[138:139] op_sel_hi:[1,0]
	s_nop 0
	v_mul_f32_e32 v37, 0xbfb8aa3b, v33
	v_exp_f32_e32 v37, v37
	s_nop 0
	v_add_f32_e32 v37, 1.0, v37
	v_rcp_f32_e32 v37, v37
	s_nop 0
	v_mul_f32_e32 v33, v33, v37
	v_mul_f32_e32 v37, v32, v33
	v_mov_b32_e32 v32, v38
	v_mov_b32_e32 v33, v46
	v_pk_mul_f32 v[32:33], v[32:33], v[138:139] op_sel_hi:[1,0]
	v_mov_b32_e32 v46, v39
	v_mul_f32_e32 v38, 0xbfb8aa3b, v33
	v_exp_f32_e32 v38, v38
	s_nop 0
	v_add_f32_e32 v38, 1.0, v38
	v_rcp_f32_e32 v38, v38
	s_nop 0
	v_mul_f32_e32 v33, v33, v38
	v_mul_f32_e32 v38, v32, v33
	v_mov_b32_e32 v32, v34
	v_mov_b32_e32 v33, v42
	v_pk_mul_f32 v[32:33], v[32:33], v[138:139] op_sel_hi:[1,0]
	v_mov_b32_e32 v42, v35
	v_mul_f32_e32 v34, 0xbfb8aa3b, v33
	v_exp_f32_e32 v34, v34
	s_nop 0
	v_add_f32_e32 v34, 1.0, v34
	v_rcp_f32_e32 v34, v34
	s_nop 0
	v_mul_f32_e32 v33, v33, v34
	v_mul_f32_e32 v40, v32, v33
	v_pk_mul_f32 v[32:33], v[46:47], v[138:139] op_sel_hi:[1,0]
	s_nop 0
	v_mul_f32_e32 v34, 0xbfb8aa3b, v33
	v_exp_f32_e32 v34, v34
	s_nop 0
	v_add_f32_e32 v34, 1.0, v34
	v_rcp_f32_e32 v34, v34
	s_nop 0
	v_mul_f32_e32 v33, v33, v34
	v_mul_f32_e32 v34, v32, v33
	v_pk_mul_f32 v[32:33], v[42:43], v[138:139] op_sel_hi:[1,0]
	s_nop 0
	v_mul_f32_e32 v35, 0xbfb8aa3b, v33
	v_exp_f32_e32 v35, v35
	s_nop 0
	v_add_f32_e32 v35, 1.0, v35
	v_rcp_f32_e32 v35, v35
	s_nop 0
	v_mul_f32_e32 v33, v33, v35
	v_mul_f32_e32 v35, v32, v33
	v_cvt_pk_bf16_f32 v32, v50, v36
	v_cvt_pk_bf16_f32 v33, v38, v34
	v_cvt_pk_bf16_f32 v34, v48, v37
	v_mad_i64_i32 v[36:37], s[0:1], v162, s11, v[114:115]
	v_lshl_add_u64 v[36:37], v[36:37], 0, v[116:117]
	v_cvt_pk_bf16_f32 v35, v40, v35
	global_store_dwordx4 v[36:37], v[32:35], off sc1
	s_nop 1
	v_mov_b32_e32 v32, v20
	v_mov_b32_e32 v33, v28
	v_pk_mul_f32 v[32:33], v[32:33], v[130:131] op_sel_hi:[1,0]
	v_mov_b32_e32 v28, v21
	v_mul_f32_e32 v20, 0xbfb8aa3b, v33
	v_exp_f32_e32 v20, v20
	s_nop 0
	v_add_f32_e32 v20, 1.0, v20
	v_rcp_f32_e32 v20, v20
	s_nop 0
	v_mul_f32_e32 v20, v33, v20
	v_mul_f32_e32 v34, v32, v20
	v_mov_b32_e32 v32, v16
	v_mov_b32_e32 v33, v24
	v_pk_mul_f32 v[32:33], v[32:33], v[130:131] op_sel_hi:[1,0]
	v_pk_mul_f32 v[20:21], v[28:29], v[130:131] op_sel_hi:[1,0]
; __device__ __forceinline__ u32x4 pack8(const f32x4 v0, const f32x4 v1) { u32x4 w; w.x = cvt_pk_bf16(v0[0], v0[1]); w.y = cvt_pk_bf16(v0[2], v0[3]); w.z = cvt_pk_bf16(v1[0], v1[1]); w.w = cvt_pk_bf16(v1[2], v1[3]); return w; }
; __device__ __forceinline__ float fsig(float v) { return __builtin_amdgcn_rcpf(1.f + __expf(-v)); }
; __device__ __forceinline__ float fsilu(float v) { return v * fsig(v); }
;     __device__ __forceinline__ void operator()(const f32x4 (&acc)[2][2][4][2], const Unit& u, int wr, int wc, int fr, int fq) const {
;     ...
;             for (int m = 0; m < 4; ++m) { const int row = row0 + ai * HALF + m * 16; const float rs = rsv[ai][m];
;                 f32x4 o0, o1;
; #pragma unroll
;                 for (int i = 0; i < 4; ++i) { o0[i] = fsilu(acc[ai][0][m][0][i] * rs) * (acc[ai][1][m][0][i] * rs); o1[i] = fsilu(acc[ai][0][m][1][i] * rs) * (acc[ai][1][m][1][i] * rs); }
;                 *(u32x4*)(H + (size_t)row * ldh + col0) = pack8(o0, o1); __builtin_amdgcn_sched_barrier(0); }
	v_mul_f32_e32 v16, 0xbfb8aa3b, v33
	v_exp_f32_e32 v16, v16
	v_mov_b32_e32 v24, v17
	v_add_f32_e32 v16, 1.0, v16
	v_rcp_f32_e32 v16, v16
	s_nop 0
	v_mul_f32_e32 v16, v33, v16
	v_mul_f32_e32 v32, v32, v16
	v_mul_f32_e32 v16, 0xbfb8aa3b, v21
	v_exp_f32_e32 v16, v16
	s_nop 0
	v_add_f32_e32 v16, 1.0, v16
	v_rcp_f32_e32 v16, v16
	s_nop 0
	v_mul_f32_e32 v16, v21, v16
	v_mul_f32_e32 v20, v20, v16
	v_pk_mul_f32 v[16:17], v[24:25], v[130:131] op_sel_hi:[1,0]
	s_nop 0
	v_mul_f32_e32 v21, 0xbfb8aa3b, v17
	v_exp_f32_e32 v21, v21
	s_nop 0
	v_add_f32_e32 v21, 1.0, v21
	v_rcp_f32_e32 v21, v21
	s_nop 0
	v_mul_f32_e32 v17, v17, v21
	v_mul_f32_e32 v21, v16, v17
	v_mov_b32_e32 v16, v22
	v_mov_b32_e32 v17, v30
	v_pk_mul_f32 v[16:17], v[16:17], v[130:131] op_sel_hi:[1,0]
	v_mov_b32_e32 v30, v23
	v_mul_f32_e32 v22, 0xbfb8aa3b, v17
	v_exp_f32_e32 v22, v22
	s_nop 0
	v_add_f32_e32 v22, 1.0, v22
	v_rcp_f32_e32 v22, v22
	s_nop 0
	v_mul_f32_e32 v17, v17, v22
	v_mul_f32_e32 v22, v16, v17
	v_mov_b32_e32 v16, v18
	v_mov_b32_e32 v17, v26
	v_pk_mul_f32 v[16:17], v[16:17], v[130:131] op_sel_hi:[1,0]
	v_mov_b32_e32 v26, v19
	v_mul_f32_e32 v18, 0xbfb8aa3b, v17
	v_exp_f32_e32 v18, v18
	s_nop 0
	v_add_f32_e32 v18, 1.0, v18
	v_rcp_f32_e32 v18, v18
	s_nop 0
	v_mul_f32_e32 v17, v17, v18
	v_mul_f32_e32 v24, v16, v17
	v_pk_mul_f32 v[16:17], v[30:31], v[130:131] op_sel_hi:[1,0]
	s_nop 0
	v_mul_f32_e32 v18, 0xbfb8aa3b, v17
	v_exp_f32_e32 v18, v18
	s_nop 0
	v_add_f32_e32 v18, 1.0, v18
	v_rcp_f32_e32 v18, v18
	s_nop 0
	v_mul_f32_e32 v17, v17, v18
	v_mul_f32_e32 v18, v16, v17
	v_pk_mul_f32 v[16:17], v[26:27], v[130:131] op_sel_hi:[1,0]
	s_nop 0
	v_mul_f32_e32 v19, 0xbfb8aa3b, v17
	v_exp_f32_e32 v19, v19
	s_nop 0
	v_add_f32_e32 v19, 1.0, v19
	v_rcp_f32_e32 v19, v19
	s_nop 0
	v_mul_f32_e32 v17, v17, v19
	v_mul_f32_e32 v19, v16, v17
	v_cvt_pk_bf16_f32 v16, v34, v20
	v_cvt_pk_bf16_f32 v17, v22, v18
	v_cvt_pk_bf16_f32 v18, v32, v21
	v_mad_i64_i32 v[20:21], s[0:1], v160, s11, v[114:115]
	v_lshl_add_u64 v[20:21], v[20:21], 0, v[116:117]
	v_cvt_pk_bf16_f32 v19, v24, v19
	global_store_dwordx4 v[20:21], v[16:19], off sc1
	s_nop 1
	v_mov_b32_e32 v16, v4
	v_mov_b32_e32 v17, v12
	v_pk_mul_f32 v[16:17], v[16:17], v[64:65] op_sel_hi:[1,0]
	v_mov_b32_e32 v12, v5
	v_mul_f32_e32 v4, 0xbfb8aa3b, v17
	v_exp_f32_e32 v4, v4
	s_nop 0
	v_add_f32_e32 v4, 1.0, v4
	v_rcp_f32_e32 v4, v4
	s_nop 0
	v_mul_f32_e32 v4, v17, v4
	v_mul_f32_e32 v18, v16, v4
	v_mov_b32_e32 v16, v0
	v_mov_b32_e32 v17, v8
	v_pk_mul_f32 v[16:17], v[16:17], v[64:65] op_sel_hi:[1,0]
	v_pk_mul_f32 v[4:5], v[12:13], v[64:65] op_sel_hi:[1,0]
	v_mul_f32_e32 v0, 0xbfb8aa3b, v17
	v_exp_f32_e32 v0, v0
	v_mov_b32_e32 v8, v1
	v_add_f32_e32 v0, 1.0, v0
	v_rcp_f32_e32 v0, v0
	s_nop 0
	v_mul_f32_e32 v0, v17, v0
	v_mul_f32_e32 v16, v16, v0
	v_mul_f32_e32 v0, 0xbfb8aa3b, v5
	v_exp_f32_e32 v0, v0
	s_nop 0
	v_add_f32_e32 v0, 1.0, v0
	v_rcp_f32_e32 v0, v0
	s_nop 0
	v_mul_f32_e32 v0, v5, v0
	v_mul_f32_e32 v4, v4, v0
	v_pk_mul_f32 v[0:1], v[8:9], v[64:65] op_sel_hi:[1,0]
	s_nop 0
	v_mul_f32_e32 v5, 0xbfb8aa3b, v1
	v_exp_f32_e32 v5, v5
	s_nop 0
	v_add_f32_e32 v5, 1.0, v5
	v_rcp_f32_e32 v5, v5
	s_nop 0
	v_mul_f32_e32 v1, v1, v5
	v_mul_f32_e32 v5, v0, v1
	v_mov_b32_e32 v0, v6
	v_mov_b32_e32 v1, v14
	v_pk_mul_f32 v[0:1], v[0:1], v[64:65] op_sel_hi:[1,0]
	v_mov_b32_e32 v14, v7
	v_mul_f32_e32 v6, 0xbfb8aa3b, v1
	v_exp_f32_e32 v6, v6
	s_nop 0
	v_add_f32_e32 v6, 1.0, v6
	v_rcp_f32_e32 v6, v6
	s_nop 0
	v_mul_f32_e32 v1, v1, v6
	v_mul_f32_e32 v6, v0, v1
	v_mov_b32_e32 v0, v2
	v_mov_b32_e32 v1, v10
	v_pk_mul_f32 v[0:1], v[0:1], v[64:65] op_sel_hi:[1,0]
	v_mov_b32_e32 v10, v3
	v_mul_f32_e32 v2, 0xbfb8aa3b, v1
	v_exp_f32_e32 v2, v2
	s_nop 0
	v_add_f32_e32 v2, 1.0, v2
	v_rcp_f32_e32 v2, v2
	s_nop 0
	v_mul_f32_e32 v1, v1, v2
	v_mul_f32_e32 v8, v0, v1
	v_pk_mul_f32 v[0:1], v[14:15], v[64:65] op_sel_hi:[1,0]
	s_nop 0
	v_mul_f32_e32 v2, 0xbfb8aa3b, v1
	v_exp_f32_e32 v2, v2
	s_nop 0
	v_add_f32_e32 v2, 1.0, v2
	v_rcp_f32_e32 v2, v2
	s_nop 0
	v_mul_f32_e32 v1, v1, v2
	v_mul_f32_e32 v2, v0, v1
	v_pk_mul_f32 v[0:1], v[10:11], v[64:65] op_sel_hi:[1,0]
	s_nop 0
	v_mul_f32_e32 v3, 0xbfb8aa3b, v1
	v_exp_f32_e32 v3, v3
	s_nop 0
	v_add_f32_e32 v3, 1.0, v3
	v_rcp_f32_e32 v3, v3
	s_nop 0
	v_mul_f32_e32 v1, v1, v3
	v_mul_f32_e32 v3, v0, v1
	v_cvt_pk_bf16_f32 v0, v18, v4
	v_cvt_pk_bf16_f32 v1, v6, v2
	v_cvt_pk_bf16_f32 v2, v16, v5
	v_mad_i64_i32 v[4:5], s[0:1], v158, s11, v[114:115]
	v_lshl_add_u64 v[4:5], v[4:5], 0, v[116:117]
	v_cvt_pk_bf16_f32 v3, v8, v3
	global_store_dwordx4 v[4:5], v[0:3], off sc1
	s_andn2_b64 vcc, exec, s[2:3]
	s_mov_b64 s[0:1], -1
	s_cbranch_vccnz .LBB0_1446
	s_andn2_b64 vcc, exec, s[6:7]
	s_cbranch_vccnz .LBB0_1445
	s_barrier
	s_branch .LBB0_1445
